# SWIGLU 256x128 tile: all A fragments register-staged so next A slab streams under the full MFMA block; B double-buffered in LDS
# speedup vs baseline: 1.4539x; 1.0131x over previous
.LBB0_139:
	s_sub_u32 s4, s0, s65
	s_lshl_b32 s4, s4, 8
	s_lshl_b32 s15, s65, 7
	s_add_u32 s14, s4, s15
	v_lshrrev_b32_e32 v132, 4, v182
	v_xor_b32_e32 v132, v132, v182
	v_and_b32_e32 v132, 7, v132
	v_lshlrev_b32_e32 v132, 4, v132
	v_lshrrev_b32_e32 v133, 3, v182
	v_lshrrev_b32_e32 v134, 6, v182
	v_lshl_or_b32 v180, v133, 11, v132
	v_readfirstlane_b32 s5, v134
	v_and_b32_e32 v135, 15, v182
	v_bfe_u32 v136, v182, 4, 2
	v_bfe_u32 v137, v182, 1, 3
	v_xor_b32_e32 v138, v136, v137
	v_or_b32_e32 v139, 4, v136
	v_xor_b32_e32 v139, v139, v137
	v_lshlrev_b32_e32 v138, 4, v138
	v_lshlrev_b32_e32 v139, 4, v139
	v_lshl_or_b32 v138, v135, 7, v138
	v_lshl_or_b32 v139, v135, 7, v139
	v_bfe_u32 v140, v182, 7, 1
	v_bfe_u32 v141, v182, 6, 1
	v_lshl_add_u32 v181, v140, 14, v138
	v_lshl_add_u32 v208, v140, 14, v139
	v_lshl_add_u32 v223, v141, 13, v138
	v_lshl_add_u32 v233, v141, 13, v139
	v_lshlrev_b32_e32 v142, 2, v136
	v_lshl_or_b32 v142, v140, 7, v142
	v_mul_u32_u24_e32 v246, 0x1600, v142
	v_lshl_or_b32 v142, v141, 5, v135
	v_lshl_add_u32 v246, v142, 1, v246
	s_lshl_b32 s5, s5, 10
	s_lshl_b32 s4, s14, 11
	s_add_u32 s8, s40, s4
	s_addc_u32 s9, s41, 0
	s_lshl_b32 s4, s13, 18
	s_add_u32 s10, s66, s4
	s_addc_u32 s11, s67, 0
	s_mul_i32 s4, s14, 0x1600
	s_lshl_b32 s15, s13, 7
	s_add_u32 s4, s4, s15
	s_add_u32 s98, s30, s4
	s_addc_u32 s99, s31, 0
	s_mov_b32 s23, 0x8000
	s_add_u32 m0, s5, 0x0
	s_nop 0
	global_load_lds_dwordx4 v180, s[8:9]
	s_add_u32 m0, s5, 0x1000
	s_add_u32 s20, s8, 0x10000
	s_addc_u32 s21, s9, 0
	global_load_lds_dwordx4 v180, s[20:21]
	s_add_u32 m0, s5, 0x2000
	s_add_u32 s20, s8, 0x20000
	s_addc_u32 s21, s9, 0
	global_load_lds_dwordx4 v180, s[20:21]
	s_add_u32 m0, s5, 0x3000
	s_add_u32 s20, s8, 0x30000
	s_addc_u32 s21, s9, 0
	global_load_lds_dwordx4 v180, s[20:21]
	s_add_u32 m0, s5, 0x4000
	s_add_u32 s20, s8, 0x40000
	s_addc_u32 s21, s9, 0
	global_load_lds_dwordx4 v180, s[20:21]
	s_add_u32 m0, s5, 0x5000
	s_add_u32 s20, s8, 0x50000
	s_addc_u32 s21, s9, 0
	global_load_lds_dwordx4 v180, s[20:21]
	s_add_u32 m0, s5, 0x6000
	s_add_u32 s20, s8, 0x60000
	s_addc_u32 s21, s9, 0
	global_load_lds_dwordx4 v180, s[20:21]
	s_add_u32 m0, s5, 0x7000
	s_add_u32 s20, s8, 0x70000
	s_addc_u32 s21, s9, 0
	global_load_lds_dwordx4 v180, s[20:21]
	s_add_u32 s8, s8, 0x80
	s_addc_u32 s9, s9, 0
	s_add_u32 m0, s5, s23
	s_nop 0
	global_load_lds_dwordx4 v180, s[10:11]
	s_add_u32 m0, m0, 0x1000
	s_add_u32 s20, s10, 0x10000
	s_addc_u32 s21, s11, 0
	global_load_lds_dwordx4 v180, s[20:21]
	s_add_u32 m0, m0, 0x1000
	s_add_u32 s20, s10, 0x20000
	s_addc_u32 s21, s11, 0
	global_load_lds_dwordx4 v180, s[20:21]
	s_add_u32 m0, m0, 0x1000
	s_add_u32 s20, s10, 0x30000
	s_addc_u32 s21, s11, 0
	global_load_lds_dwordx4 v180, s[20:21]
	s_add_u32 s10, s10, 0x80
	s_addc_u32 s11, s11, 0
	v_mov_b32_e32 v0, 0
	v_mov_b32_e32 v1, v0
	v_mov_b32_e32 v2, v0
	v_mov_b32_e32 v3, v0
	v_mov_b32_e32 v4, v0
	v_mov_b32_e32 v5, v0
	v_mov_b32_e32 v6, v0
	v_mov_b32_e32 v7, v0
	v_mov_b32_e32 v8, v0
	v_mov_b32_e32 v9, v0
	v_mov_b32_e32 v10, v0
	v_mov_b32_e32 v11, v0
	v_mov_b32_e32 v12, v0
	v_mov_b32_e32 v13, v0
	v_mov_b32_e32 v14, v0
	v_mov_b32_e32 v15, v0
	v_mov_b32_e32 v16, v0
	v_mov_b32_e32 v17, v0
	v_mov_b32_e32 v18, v0
	v_mov_b32_e32 v19, v0
	v_mov_b32_e32 v20, v0
	v_mov_b32_e32 v21, v0
	v_mov_b32_e32 v22, v0
	v_mov_b32_e32 v23, v0
	v_mov_b32_e32 v24, v0
	v_mov_b32_e32 v25, v0
	v_mov_b32_e32 v26, v0
	v_mov_b32_e32 v27, v0
	v_mov_b32_e32 v28, v0
	v_mov_b32_e32 v29, v0
	v_mov_b32_e32 v30, v0
	v_mov_b32_e32 v31, v0
	v_mov_b32_e32 v32, v0
	v_mov_b32_e32 v33, v0
	v_mov_b32_e32 v34, v0
	v_mov_b32_e32 v35, v0
	v_mov_b32_e32 v36, v0
	v_mov_b32_e32 v37, v0
	v_mov_b32_e32 v38, v0
	v_mov_b32_e32 v39, v0
	v_mov_b32_e32 v40, v0
	v_mov_b32_e32 v41, v0
	v_mov_b32_e32 v42, v0
	v_mov_b32_e32 v43, v0
	v_mov_b32_e32 v44, v0
	v_mov_b32_e32 v45, v0
	v_mov_b32_e32 v46, v0
	v_mov_b32_e32 v47, v0
	v_mov_b32_e32 v48, v0
	v_mov_b32_e32 v49, v0
	v_mov_b32_e32 v50, v0
	v_mov_b32_e32 v51, v0
	v_mov_b32_e32 v52, v0
	v_mov_b32_e32 v53, v0
	v_mov_b32_e32 v54, v0
	v_mov_b32_e32 v55, v0
	v_mov_b32_e32 v56, v0
	v_mov_b32_e32 v57, v0
	v_mov_b32_e32 v58, v0
	v_mov_b32_e32 v59, v0
	v_mov_b32_e32 v60, v0
	v_mov_b32_e32 v61, v0
	v_mov_b32_e32 v62, v0
	v_mov_b32_e32 v63, v0
	v_mov_b32_e32 v64, v0
	v_mov_b32_e32 v65, v0
	v_mov_b32_e32 v66, v0
	v_mov_b32_e32 v67, v0
	v_mov_b32_e32 v68, v0
	v_mov_b32_e32 v69, v0
	v_mov_b32_e32 v70, v0
	v_mov_b32_e32 v71, v0
	v_mov_b32_e32 v72, v0
	v_mov_b32_e32 v73, v0
	v_mov_b32_e32 v74, v0
	v_mov_b32_e32 v75, v0
	v_mov_b32_e32 v76, v0
	v_mov_b32_e32 v77, v0
	v_mov_b32_e32 v78, v0
	v_mov_b32_e32 v79, v0
	v_mov_b32_e32 v80, v0
	v_mov_b32_e32 v81, v0
	v_mov_b32_e32 v82, v0
	v_mov_b32_e32 v83, v0
	v_mov_b32_e32 v84, v0
	v_mov_b32_e32 v85, v0
	v_mov_b32_e32 v86, v0
	v_mov_b32_e32 v87, v0
	v_mov_b32_e32 v88, v0
	v_mov_b32_e32 v89, v0
	v_mov_b32_e32 v90, v0
	v_mov_b32_e32 v91, v0
	v_mov_b32_e32 v92, v0
	v_mov_b32_e32 v93, v0
	v_mov_b32_e32 v94, v0
	v_mov_b32_e32 v95, v0
	v_mov_b32_e32 v96, v0
	v_mov_b32_e32 v97, v0
	v_mov_b32_e32 v98, v0
	v_mov_b32_e32 v99, v0
	v_mov_b32_e32 v100, v0
	v_mov_b32_e32 v101, v0
	v_mov_b32_e32 v102, v0
	v_mov_b32_e32 v103, v0
	v_mov_b32_e32 v104, v0
	v_mov_b32_e32 v105, v0
	v_mov_b32_e32 v106, v0
	v_mov_b32_e32 v107, v0
	v_mov_b32_e32 v108, v0
	v_mov_b32_e32 v109, v0
	v_mov_b32_e32 v110, v0
	v_mov_b32_e32 v111, v0
	v_mov_b32_e32 v116, v0
	v_mov_b32_e32 v117, v0
	v_mov_b32_e32 v118, v0
	v_mov_b32_e32 v119, v0
	v_mov_b32_e32 v120, v0
	v_mov_b32_e32 v121, v0
	v_mov_b32_e32 v122, v0
	v_mov_b32_e32 v123, v0
	v_mov_b32_e32 v124, v0
	v_mov_b32_e32 v125, v0
	v_mov_b32_e32 v126, v0
	v_mov_b32_e32 v127, v0
	v_mov_b32_e32 v128, v0
	v_mov_b32_e32 v129, v0
	v_mov_b32_e32 v130, v0
	v_mov_b32_e32 v131, v0
	s_movk_i32 s16, 15
.Lg3_sw1:
	s_waitcnt vmcnt(0)
	s_barrier
	s_xor_b32 s23, s23, 0x4000
	s_cmp_eq_u32 s16, 0
	s_cbranch_scc1 .Lg3_sw1_nb
	s_add_u32 m0, s5, s23
	s_nop 0
	global_load_lds_dwordx4 v180, s[10:11]
	s_add_u32 m0, m0, 0x1000
	s_add_u32 s20, s10, 0x10000
	s_addc_u32 s21, s11, 0
	global_load_lds_dwordx4 v180, s[20:21]
	s_add_u32 m0, m0, 0x1000
	s_add_u32 s20, s10, 0x20000
	s_addc_u32 s21, s11, 0
	global_load_lds_dwordx4 v180, s[20:21]
	s_add_u32 m0, m0, 0x1000
	s_add_u32 s20, s10, 0x30000
	s_addc_u32 s21, s11, 0
	global_load_lds_dwordx4 v180, s[20:21]
	s_add_u32 s10, s10, 0x80
	s_addc_u32 s11, s11, 0
.Lg3_sw1_nb:
	ds_read_b128 v[132:135], v181 offset:0
	ds_read_b128 v[136:139], v181 offset:2048
	ds_read_b128 v[140:143], v181 offset:4096
	ds_read_b128 v[144:147], v181 offset:6144
	ds_read_b128 v[148:151], v181 offset:8192
	ds_read_b128 v[152:155], v181 offset:10240
	ds_read_b128 v[156:159], v181 offset:12288
	ds_read_b128 v[160:163], v181 offset:14336
	ds_read_b128 v[164:167], v208 offset:0
	ds_read_b128 v[168:171], v208 offset:2048
	ds_read_b128 v[172:175], v208 offset:4096
	ds_read_b128 v[176:179], v208 offset:6144
	ds_read_b128 v[224:227], v208 offset:8192
	ds_read_b128 v[228:231], v208 offset:10240
	s_waitcnt lgkmcnt(6)
	ds_read_b128 v[234:237], v208 offset:12288
	ds_read_b128 v[238:241], v208 offset:14336
	ds_read_b128 v[242:245], v223 offset:32768
	ds_read_b128 v[112:115], v223 offset:34816
	s_waitcnt lgkmcnt(2)
	s_barrier
	s_cmp_eq_u32 s16, 0
	s_cbranch_scc1 .Lg3_sw1_nl
	s_add_u32 m0, s5, 0x0
	s_nop 0
	global_load_lds_dwordx4 v180, s[8:9]
	s_add_u32 m0, s5, 0x1000
	s_add_u32 s20, s8, 0x10000
	s_addc_u32 s21, s9, 0
	global_load_lds_dwordx4 v180, s[20:21]
	s_add_u32 m0, s5, 0x2000
	s_add_u32 s20, s8, 0x20000
	s_addc_u32 s21, s9, 0
	global_load_lds_dwordx4 v180, s[20:21]
	s_add_u32 m0, s5, 0x3000
	s_add_u32 s20, s8, 0x30000
	s_addc_u32 s21, s9, 0
	global_load_lds_dwordx4 v180, s[20:21]
	s_add_u32 m0, s5, 0x4000
	s_add_u32 s20, s8, 0x40000
	s_addc_u32 s21, s9, 0
	global_load_lds_dwordx4 v180, s[20:21]
	s_add_u32 m0, s5, 0x5000
	s_add_u32 s20, s8, 0x50000
	s_addc_u32 s21, s9, 0
	global_load_lds_dwordx4 v180, s[20:21]
	s_add_u32 m0, s5, 0x6000
	s_add_u32 s20, s8, 0x60000
	s_addc_u32 s21, s9, 0
	global_load_lds_dwordx4 v180, s[20:21]
	s_add_u32 m0, s5, 0x7000
	s_add_u32 s20, s8, 0x70000
	s_addc_u32 s21, s9, 0
	global_load_lds_dwordx4 v180, s[20:21]
	s_add_u32 s8, s8, 0x80
	s_addc_u32 s9, s9, 0
.Lg3_sw1_nl:
	s_waitcnt lgkmcnt(1)
	v_mfma_f32_16x16x32_f16 v[0:3], v[132:135], v[242:245], v[0:3]
	v_mfma_f32_16x16x32_f16 v[16:19], v[136:139], v[242:245], v[16:19]
	v_mfma_f32_16x16x32_f16 v[32:35], v[140:143], v[242:245], v[32:35]
	v_mfma_f32_16x16x32_f16 v[48:51], v[144:147], v[242:245], v[48:51]
	v_mfma_f32_16x16x32_f16 v[64:67], v[148:151], v[242:245], v[64:67]
	v_mfma_f32_16x16x32_f16 v[80:83], v[152:155], v[242:245], v[80:83]
	v_mfma_f32_16x16x32_f16 v[96:99], v[156:159], v[242:245], v[96:99]
	v_mfma_f32_16x16x32_f16 v[116:119], v[160:163], v[242:245], v[116:119]
	ds_read_b128 v[242:245], v223 offset:36864
	s_waitcnt lgkmcnt(1)
	v_mfma_f32_16x16x32_f16 v[4:7], v[132:135], v[112:115], v[4:7]
	v_mfma_f32_16x16x32_f16 v[20:23], v[136:139], v[112:115], v[20:23]
	v_mfma_f32_16x16x32_f16 v[36:39], v[140:143], v[112:115], v[36:39]
	v_mfma_f32_16x16x32_f16 v[52:55], v[144:147], v[112:115], v[52:55]
	v_mfma_f32_16x16x32_f16 v[68:71], v[148:151], v[112:115], v[68:71]
	v_mfma_f32_16x16x32_f16 v[84:87], v[152:155], v[112:115], v[84:87]
	v_mfma_f32_16x16x32_f16 v[100:103], v[156:159], v[112:115], v[100:103]
	v_mfma_f32_16x16x32_f16 v[120:123], v[160:163], v[112:115], v[120:123]
	ds_read_b128 v[112:115], v223 offset:38912
	s_waitcnt lgkmcnt(1)
	v_mfma_f32_16x16x32_f16 v[8:11], v[132:135], v[242:245], v[8:11]
	v_mfma_f32_16x16x32_f16 v[24:27], v[136:139], v[242:245], v[24:27]
	v_mfma_f32_16x16x32_f16 v[40:43], v[140:143], v[242:245], v[40:43]
	v_mfma_f32_16x16x32_f16 v[56:59], v[144:147], v[242:245], v[56:59]
	v_mfma_f32_16x16x32_f16 v[72:75], v[148:151], v[242:245], v[72:75]
	v_mfma_f32_16x16x32_f16 v[88:91], v[152:155], v[242:245], v[88:91]
	v_mfma_f32_16x16x32_f16 v[104:107], v[156:159], v[242:245], v[104:107]
	v_mfma_f32_16x16x32_f16 v[124:127], v[160:163], v[242:245], v[124:127]
	ds_read_b128 v[242:245], v233 offset:32768
	s_waitcnt lgkmcnt(1)
	v_mfma_f32_16x16x32_f16 v[12:15], v[132:135], v[112:115], v[12:15]
	v_mfma_f32_16x16x32_f16 v[28:31], v[136:139], v[112:115], v[28:31]
	v_mfma_f32_16x16x32_f16 v[44:47], v[140:143], v[112:115], v[44:47]
	v_mfma_f32_16x16x32_f16 v[60:63], v[144:147], v[112:115], v[60:63]
	v_mfma_f32_16x16x32_f16 v[76:79], v[148:151], v[112:115], v[76:79]
	v_mfma_f32_16x16x32_f16 v[92:95], v[152:155], v[112:115], v[92:95]
	v_mfma_f32_16x16x32_f16 v[108:111], v[156:159], v[112:115], v[108:111]
	v_mfma_f32_16x16x32_f16 v[128:131], v[160:163], v[112:115], v[128:131]
	ds_read_b128 v[112:115], v233 offset:34816
	s_waitcnt lgkmcnt(1)
	v_mfma_f32_16x16x32_f16 v[0:3], v[164:167], v[242:245], v[0:3]
	v_mfma_f32_16x16x32_f16 v[16:19], v[168:171], v[242:245], v[16:19]
	v_mfma_f32_16x16x32_f16 v[32:35], v[172:175], v[242:245], v[32:35]
	v_mfma_f32_16x16x32_f16 v[48:51], v[176:179], v[242:245], v[48:51]
	v_mfma_f32_16x16x32_f16 v[64:67], v[224:227], v[242:245], v[64:67]
	v_mfma_f32_16x16x32_f16 v[80:83], v[228:231], v[242:245], v[80:83]
	v_mfma_f32_16x16x32_f16 v[96:99], v[234:237], v[242:245], v[96:99]
	v_mfma_f32_16x16x32_f16 v[116:119], v[238:241], v[242:245], v[116:119]
	ds_read_b128 v[242:245], v233 offset:36864
	s_waitcnt lgkmcnt(1)
	v_mfma_f32_16x16x32_f16 v[4:7], v[164:167], v[112:115], v[4:7]
	v_mfma_f32_16x16x32_f16 v[20:23], v[168:171], v[112:115], v[20:23]
	v_mfma_f32_16x16x32_f16 v[36:39], v[172:175], v[112:115], v[36:39]
	v_mfma_f32_16x16x32_f16 v[52:55], v[176:179], v[112:115], v[52:55]
	v_mfma_f32_16x16x32_f16 v[68:71], v[224:227], v[112:115], v[68:71]
	v_mfma_f32_16x16x32_f16 v[84:87], v[228:231], v[112:115], v[84:87]
	v_mfma_f32_16x16x32_f16 v[100:103], v[234:237], v[112:115], v[100:103]
	v_mfma_f32_16x16x32_f16 v[120:123], v[238:241], v[112:115], v[120:123]
	ds_read_b128 v[112:115], v233 offset:38912
	s_waitcnt lgkmcnt(1)
	v_mfma_f32_16x16x32_f16 v[8:11], v[164:167], v[242:245], v[8:11]
	v_mfma_f32_16x16x32_f16 v[24:27], v[168:171], v[242:245], v[24:27]
	v_mfma_f32_16x16x32_f16 v[40:43], v[172:175], v[242:245], v[40:43]
	v_mfma_f32_16x16x32_f16 v[56:59], v[176:179], v[242:245], v[56:59]
	v_mfma_f32_16x16x32_f16 v[72:75], v[224:227], v[242:245], v[72:75]
	v_mfma_f32_16x16x32_f16 v[88:91], v[228:231], v[242:245], v[88:91]
	v_mfma_f32_16x16x32_f16 v[104:107], v[234:237], v[242:245], v[104:107]
	v_mfma_f32_16x16x32_f16 v[124:127], v[238:241], v[242:245], v[124:127]
	s_waitcnt lgkmcnt(0)
	v_mfma_f32_16x16x32_f16 v[12:15], v[164:167], v[112:115], v[12:15]
	v_mfma_f32_16x16x32_f16 v[28:31], v[168:171], v[112:115], v[28:31]
	v_mfma_f32_16x16x32_f16 v[44:47], v[172:175], v[112:115], v[44:47]
	v_mfma_f32_16x16x32_f16 v[60:63], v[176:179], v[112:115], v[60:63]
	v_mfma_f32_16x16x32_f16 v[76:79], v[224:227], v[112:115], v[76:79]
	v_mfma_f32_16x16x32_f16 v[92:95], v[228:231], v[112:115], v[92:95]
	v_mfma_f32_16x16x32_f16 v[108:111], v[234:237], v[112:115], v[108:111]
	v_mfma_f32_16x16x32_f16 v[128:131], v[238:241], v[112:115], v[128:131]
	v_xor_b32_e32 v223, 0x4000, v223
	v_xor_b32_e32 v233, 0x4000, v233
	s_sub_u32 s16, s16, 1
	s_cmp_lg_u32 s16, -1
	s_cbranch_scc1 .Lg3_sw1
	s_nop 7
	s_mov_b64 s[100:101], s[98:99]
	v_mul_f32_e32 v132, 0xbfb8aa3b, v0
	v_exp_f32_e32 v132, v132
	s_nop 0
	v_add_f32_e32 v133, 1.0, v132
	v_div_scale_f32 v134, s[8:9], v133, v133, v0
	v_rcp_f32_e32 v135, v134
	v_div_scale_f32 v136, vcc, v0, v133, v0
	v_fma_f32 v137, -v134, v135, 1.0
	v_fmac_f32_e32 v135, v137, v135
	v_mul_f32_e32 v138, v136, v135
	v_fma_f32 v137, -v134, v138, v136
	v_fmac_f32_e32 v138, v137, v135
	v_fma_f32 v134, -v134, v138, v136
	v_div_fmas_f32 v134, v134, v135, v138
	v_div_fixup_f32 v134, v134, v133, v0
	v_mul_f32_e32 v134, v8, v134
	v_med3_f32 v134, v134, s57, v194
	v_cvt_f16_f32_e32 v139, v134
	v_mul_f32_e32 v132, 0xbfb8aa3b, v4
	v_exp_f32_e32 v132, v132
	s_nop 0
	v_add_f32_e32 v133, 1.0, v132
	v_div_scale_f32 v134, s[8:9], v133, v133, v4
	v_rcp_f32_e32 v135, v134
	v_div_scale_f32 v136, vcc, v4, v133, v4
	v_fma_f32 v137, -v134, v135, 1.0
	v_fmac_f32_e32 v135, v137, v135
	v_mul_f32_e32 v138, v136, v135
	v_fma_f32 v137, -v134, v138, v136
	v_fmac_f32_e32 v138, v137, v135
	v_fma_f32 v134, -v134, v138, v136
	v_div_fmas_f32 v134, v134, v135, v138
	v_div_fixup_f32 v134, v134, v133, v4
	v_mul_f32_e32 v134, v12, v134
	v_med3_f32 v134, v134, s57, v194
	v_cvt_f16_f32_e32 v140, v134
	global_store_short v246, v139, s[100:101]
	global_store_short v246, v140, s[100:101] offset:32
	s_add_u32 s100, s98, 0x1600
	s_addc_u32 s101, s99, 0
	v_mul_f32_e32 v132, 0xbfb8aa3b, v1
	v_exp_f32_e32 v132, v132
	s_nop 0
	v_add_f32_e32 v133, 1.0, v132
	v_div_scale_f32 v134, s[8:9], v133, v133, v1
	v_rcp_f32_e32 v135, v134
	v_div_scale_f32 v136, vcc, v1, v133, v1
	v_fma_f32 v137, -v134, v135, 1.0
	v_fmac_f32_e32 v135, v137, v135
	v_mul_f32_e32 v138, v136, v135
	v_fma_f32 v137, -v134, v138, v136
	v_fmac_f32_e32 v138, v137, v135
	v_fma_f32 v134, -v134, v138, v136
	v_div_fmas_f32 v134, v134, v135, v138
	v_div_fixup_f32 v134, v134, v133, v1
	v_mul_f32_e32 v134, v9, v134
	v_med3_f32 v134, v134, s57, v194
	v_cvt_f16_f32_e32 v139, v134
	v_mul_f32_e32 v132, 0xbfb8aa3b, v5
	v_exp_f32_e32 v132, v132
	s_nop 0
	v_add_f32_e32 v133, 1.0, v132
	v_div_scale_f32 v134, s[8:9], v133, v133, v5
	v_rcp_f32_e32 v135, v134
	v_div_scale_f32 v136, vcc, v5, v133, v5
	v_fma_f32 v137, -v134, v135, 1.0
	v_fmac_f32_e32 v135, v137, v135
	v_mul_f32_e32 v138, v136, v135
	v_fma_f32 v137, -v134, v138, v136
	v_fmac_f32_e32 v138, v137, v135
	v_fma_f32 v134, -v134, v138, v136
	v_div_fmas_f32 v134, v134, v135, v138
	v_div_fixup_f32 v134, v134, v133, v5
	v_mul_f32_e32 v134, v13, v134
	v_med3_f32 v134, v134, s57, v194
	v_cvt_f16_f32_e32 v140, v134
	global_store_short v246, v139, s[100:101]
	global_store_short v246, v140, s[100:101] offset:32
	s_add_u32 s100, s98, 0x2c00
	s_addc_u32 s101, s99, 0
	v_mul_f32_e32 v132, 0xbfb8aa3b, v2
	v_exp_f32_e32 v132, v132
	s_nop 0
	v_add_f32_e32 v133, 1.0, v132
	v_div_scale_f32 v134, s[8:9], v133, v133, v2
	v_rcp_f32_e32 v135, v134
	v_div_scale_f32 v136, vcc, v2, v133, v2
	v_fma_f32 v137, -v134, v135, 1.0
	v_fmac_f32_e32 v135, v137, v135
	v_mul_f32_e32 v138, v136, v135
	v_fma_f32 v137, -v134, v138, v136
	v_fmac_f32_e32 v138, v137, v135
	v_fma_f32 v134, -v134, v138, v136
	v_div_fmas_f32 v134, v134, v135, v138
	v_div_fixup_f32 v134, v134, v133, v2
	v_mul_f32_e32 v134, v10, v134
	v_med3_f32 v134, v134, s57, v194
	v_cvt_f16_f32_e32 v139, v134
	v_mul_f32_e32 v132, 0xbfb8aa3b, v6
	v_exp_f32_e32 v132, v132
	s_nop 0
	v_add_f32_e32 v133, 1.0, v132
	v_div_scale_f32 v134, s[8:9], v133, v133, v6
	v_rcp_f32_e32 v135, v134
	v_div_scale_f32 v136, vcc, v6, v133, v6
	v_fma_f32 v137, -v134, v135, 1.0
	v_fmac_f32_e32 v135, v137, v135
	v_mul_f32_e32 v138, v136, v135
	v_fma_f32 v137, -v134, v138, v136
	v_fmac_f32_e32 v138, v137, v135
	v_fma_f32 v134, -v134, v138, v136
	v_div_fmas_f32 v134, v134, v135, v138
	v_div_fixup_f32 v134, v134, v133, v6
	v_mul_f32_e32 v134, v14, v134
	v_med3_f32 v134, v134, s57, v194
	v_cvt_f16_f32_e32 v140, v134
	global_store_short v246, v139, s[100:101]
	global_store_short v246, v140, s[100:101] offset:32
	s_add_u32 s100, s98, 0x4200
	s_addc_u32 s101, s99, 0
	v_mul_f32_e32 v132, 0xbfb8aa3b, v3
	v_exp_f32_e32 v132, v132
	s_nop 0
	v_add_f32_e32 v133, 1.0, v132
	v_div_scale_f32 v134, s[8:9], v133, v133, v3
	v_rcp_f32_e32 v135, v134
	v_div_scale_f32 v136, vcc, v3, v133, v3
	v_fma_f32 v137, -v134, v135, 1.0
	v_fmac_f32_e32 v135, v137, v135
	v_mul_f32_e32 v138, v136, v135
	v_fma_f32 v137, -v134, v138, v136
	v_fmac_f32_e32 v138, v137, v135
	v_fma_f32 v134, -v134, v138, v136
	v_div_fmas_f32 v134, v134, v135, v138
	v_div_fixup_f32 v134, v134, v133, v3
	v_mul_f32_e32 v134, v11, v134
	v_med3_f32 v134, v134, s57, v194
	v_cvt_f16_f32_e32 v139, v134
	v_mul_f32_e32 v132, 0xbfb8aa3b, v7
	v_exp_f32_e32 v132, v132
	s_nop 0
	v_add_f32_e32 v133, 1.0, v132
	v_div_scale_f32 v134, s[8:9], v133, v133, v7
	v_rcp_f32_e32 v135, v134
	v_div_scale_f32 v136, vcc, v7, v133, v7
	v_fma_f32 v137, -v134, v135, 1.0
	v_fmac_f32_e32 v135, v137, v135
	v_mul_f32_e32 v138, v136, v135
	v_fma_f32 v137, -v134, v138, v136
	v_fmac_f32_e32 v138, v137, v135
	v_fma_f32 v134, -v134, v138, v136
	v_div_fmas_f32 v134, v134, v135, v138
	v_div_fixup_f32 v134, v134, v133, v7
	v_mul_f32_e32 v134, v15, v134
	v_med3_f32 v134, v134, s57, v194
	v_cvt_f16_f32_e32 v140, v134
	global_store_short v246, v139, s[100:101]
	global_store_short v246, v140, s[100:101] offset:32
	s_add_u32 s100, s98, 0x16000
	s_addc_u32 s101, s99, 0
	v_mul_f32_e32 v132, 0xbfb8aa3b, v16
	v_exp_f32_e32 v132, v132
	s_nop 0
	v_add_f32_e32 v133, 1.0, v132
	v_div_scale_f32 v134, s[8:9], v133, v133, v16
	v_rcp_f32_e32 v135, v134
	v_div_scale_f32 v136, vcc, v16, v133, v16
	v_fma_f32 v137, -v134, v135, 1.0
	v_fmac_f32_e32 v135, v137, v135
	v_mul_f32_e32 v138, v136, v135
	v_fma_f32 v137, -v134, v138, v136
	v_fmac_f32_e32 v138, v137, v135
	v_fma_f32 v134, -v134, v138, v136
	v_div_fmas_f32 v134, v134, v135, v138
	v_div_fixup_f32 v134, v134, v133, v16
	v_mul_f32_e32 v134, v24, v134
	v_med3_f32 v134, v134, s57, v194
	v_cvt_f16_f32_e32 v139, v134
	v_mul_f32_e32 v132, 0xbfb8aa3b, v20
	v_exp_f32_e32 v132, v132
	s_nop 0
	v_add_f32_e32 v133, 1.0, v132
	v_div_scale_f32 v134, s[8:9], v133, v133, v20
	v_rcp_f32_e32 v135, v134
	v_div_scale_f32 v136, vcc, v20, v133, v20
	v_fma_f32 v137, -v134, v135, 1.0
	v_fmac_f32_e32 v135, v137, v135
	v_mul_f32_e32 v138, v136, v135
	v_fma_f32 v137, -v134, v138, v136
	v_fmac_f32_e32 v138, v137, v135
	v_fma_f32 v134, -v134, v138, v136
	v_div_fmas_f32 v134, v134, v135, v138
	v_div_fixup_f32 v134, v134, v133, v20
	v_mul_f32_e32 v134, v28, v134
	v_med3_f32 v134, v134, s57, v194
	v_cvt_f16_f32_e32 v140, v134
	global_store_short v246, v139, s[100:101]
	global_store_short v246, v140, s[100:101] offset:32
	s_add_u32 s100, s98, 0x17600
	s_addc_u32 s101, s99, 0
	v_mul_f32_e32 v132, 0xbfb8aa3b, v17
	v_exp_f32_e32 v132, v132
	s_nop 0
	v_add_f32_e32 v133, 1.0, v132
	v_div_scale_f32 v134, s[8:9], v133, v133, v17
	v_rcp_f32_e32 v135, v134
	v_div_scale_f32 v136, vcc, v17, v133, v17
	v_fma_f32 v137, -v134, v135, 1.0
	v_fmac_f32_e32 v135, v137, v135
	v_mul_f32_e32 v138, v136, v135
	v_fma_f32 v137, -v134, v138, v136
	v_fmac_f32_e32 v138, v137, v135
	v_fma_f32 v134, -v134, v138, v136
	v_div_fmas_f32 v134, v134, v135, v138
	v_div_fixup_f32 v134, v134, v133, v17
	v_mul_f32_e32 v134, v25, v134
	v_med3_f32 v134, v134, s57, v194
	v_cvt_f16_f32_e32 v139, v134
	v_mul_f32_e32 v132, 0xbfb8aa3b, v21
	v_exp_f32_e32 v132, v132
	s_nop 0
	v_add_f32_e32 v133, 1.0, v132
	v_div_scale_f32 v134, s[8:9], v133, v133, v21
	v_rcp_f32_e32 v135, v134
	v_div_scale_f32 v136, vcc, v21, v133, v21
	v_fma_f32 v137, -v134, v135, 1.0
	v_fmac_f32_e32 v135, v137, v135
	v_mul_f32_e32 v138, v136, v135
	v_fma_f32 v137, -v134, v138, v136
	v_fmac_f32_e32 v138, v137, v135
	v_fma_f32 v134, -v134, v138, v136
	v_div_fmas_f32 v134, v134, v135, v138
	v_div_fixup_f32 v134, v134, v133, v21
	v_mul_f32_e32 v134, v29, v134
	v_med3_f32 v134, v134, s57, v194
	v_cvt_f16_f32_e32 v140, v134
	global_store_short v246, v139, s[100:101]
	global_store_short v246, v140, s[100:101] offset:32
	s_add_u32 s100, s98, 0x18c00
	s_addc_u32 s101, s99, 0
	v_mul_f32_e32 v132, 0xbfb8aa3b, v18
	v_exp_f32_e32 v132, v132
	s_nop 0
	v_add_f32_e32 v133, 1.0, v132
	v_div_scale_f32 v134, s[8:9], v133, v133, v18
	v_rcp_f32_e32 v135, v134
	v_div_scale_f32 v136, vcc, v18, v133, v18
	v_fma_f32 v137, -v134, v135, 1.0
	v_fmac_f32_e32 v135, v137, v135
	v_mul_f32_e32 v138, v136, v135
	v_fma_f32 v137, -v134, v138, v136
	v_fmac_f32_e32 v138, v137, v135
	v_fma_f32 v134, -v134, v138, v136
	v_div_fmas_f32 v134, v134, v135, v138
	v_div_fixup_f32 v134, v134, v133, v18
	v_mul_f32_e32 v134, v26, v134
	v_med3_f32 v134, v134, s57, v194
	v_cvt_f16_f32_e32 v139, v134
	v_mul_f32_e32 v132, 0xbfb8aa3b, v22
	v_exp_f32_e32 v132, v132
	s_nop 0
	v_add_f32_e32 v133, 1.0, v132
	v_div_scale_f32 v134, s[8:9], v133, v133, v22
	v_rcp_f32_e32 v135, v134
	v_div_scale_f32 v136, vcc, v22, v133, v22
	v_fma_f32 v137, -v134, v135, 1.0
	v_fmac_f32_e32 v135, v137, v135
	v_mul_f32_e32 v138, v136, v135
	v_fma_f32 v137, -v134, v138, v136
	v_fmac_f32_e32 v138, v137, v135
	v_fma_f32 v134, -v134, v138, v136
	v_div_fmas_f32 v134, v134, v135, v138
	v_div_fixup_f32 v134, v134, v133, v22
	v_mul_f32_e32 v134, v30, v134
	v_med3_f32 v134, v134, s57, v194
	v_cvt_f16_f32_e32 v140, v134
	global_store_short v246, v139, s[100:101]
	global_store_short v246, v140, s[100:101] offset:32
	s_add_u32 s100, s98, 0x1a200
	s_addc_u32 s101, s99, 0
	v_mul_f32_e32 v132, 0xbfb8aa3b, v19
	v_exp_f32_e32 v132, v132
	s_nop 0
	v_add_f32_e32 v133, 1.0, v132
	v_div_scale_f32 v134, s[8:9], v133, v133, v19
	v_rcp_f32_e32 v135, v134
	v_div_scale_f32 v136, vcc, v19, v133, v19
	v_fma_f32 v137, -v134, v135, 1.0
	v_fmac_f32_e32 v135, v137, v135
	v_mul_f32_e32 v138, v136, v135
	v_fma_f32 v137, -v134, v138, v136
	v_fmac_f32_e32 v138, v137, v135
	v_fma_f32 v134, -v134, v138, v136
	v_div_fmas_f32 v134, v134, v135, v138
	v_div_fixup_f32 v134, v134, v133, v19
	v_mul_f32_e32 v134, v27, v134
	v_med3_f32 v134, v134, s57, v194
	v_cvt_f16_f32_e32 v139, v134
	v_mul_f32_e32 v132, 0xbfb8aa3b, v23
	v_exp_f32_e32 v132, v132
	s_nop 0
	v_add_f32_e32 v133, 1.0, v132
	v_div_scale_f32 v134, s[8:9], v133, v133, v23
	v_rcp_f32_e32 v135, v134
	v_div_scale_f32 v136, vcc, v23, v133, v23
	v_fma_f32 v137, -v134, v135, 1.0
	v_fmac_f32_e32 v135, v137, v135
	v_mul_f32_e32 v138, v136, v135
	v_fma_f32 v137, -v134, v138, v136
	v_fmac_f32_e32 v138, v137, v135
	v_fma_f32 v134, -v134, v138, v136
	v_div_fmas_f32 v134, v134, v135, v138
	v_div_fixup_f32 v134, v134, v133, v23
	v_mul_f32_e32 v134, v31, v134
	v_med3_f32 v134, v134, s57, v194
	v_cvt_f16_f32_e32 v140, v134
	global_store_short v246, v139, s[100:101]
	global_store_short v246, v140, s[100:101] offset:32
	s_add_u32 s100, s98, 0x2c000
	s_addc_u32 s101, s99, 0
	v_mul_f32_e32 v132, 0xbfb8aa3b, v32
	v_exp_f32_e32 v132, v132
	s_nop 0
	v_add_f32_e32 v133, 1.0, v132
	v_div_scale_f32 v134, s[8:9], v133, v133, v32
	v_rcp_f32_e32 v135, v134
	v_div_scale_f32 v136, vcc, v32, v133, v32
	v_fma_f32 v137, -v134, v135, 1.0
	v_fmac_f32_e32 v135, v137, v135
	v_mul_f32_e32 v138, v136, v135
	v_fma_f32 v137, -v134, v138, v136
	v_fmac_f32_e32 v138, v137, v135
	v_fma_f32 v134, -v134, v138, v136
	v_div_fmas_f32 v134, v134, v135, v138
	v_div_fixup_f32 v134, v134, v133, v32
	v_mul_f32_e32 v134, v40, v134
	v_med3_f32 v134, v134, s57, v194
	v_cvt_f16_f32_e32 v139, v134
	v_mul_f32_e32 v132, 0xbfb8aa3b, v36
	v_exp_f32_e32 v132, v132
	s_nop 0
	v_add_f32_e32 v133, 1.0, v132
	v_div_scale_f32 v134, s[8:9], v133, v133, v36
	v_rcp_f32_e32 v135, v134
	v_div_scale_f32 v136, vcc, v36, v133, v36
	v_fma_f32 v137, -v134, v135, 1.0
	v_fmac_f32_e32 v135, v137, v135
	v_mul_f32_e32 v138, v136, v135
	v_fma_f32 v137, -v134, v138, v136
	v_fmac_f32_e32 v138, v137, v135
	v_fma_f32 v134, -v134, v138, v136
	v_div_fmas_f32 v134, v134, v135, v138
	v_div_fixup_f32 v134, v134, v133, v36
	v_mul_f32_e32 v134, v44, v134
	v_med3_f32 v134, v134, s57, v194
	v_cvt_f16_f32_e32 v140, v134
	global_store_short v246, v139, s[100:101]
	global_store_short v246, v140, s[100:101] offset:32
	s_add_u32 s100, s98, 0x2d600
	s_addc_u32 s101, s99, 0
	v_mul_f32_e32 v132, 0xbfb8aa3b, v33
	v_exp_f32_e32 v132, v132
	s_nop 0
	v_add_f32_e32 v133, 1.0, v132
	v_div_scale_f32 v134, s[8:9], v133, v133, v33
	v_rcp_f32_e32 v135, v134
	v_div_scale_f32 v136, vcc, v33, v133, v33
	v_fma_f32 v137, -v134, v135, 1.0
	v_fmac_f32_e32 v135, v137, v135
	v_mul_f32_e32 v138, v136, v135
	v_fma_f32 v137, -v134, v138, v136
	v_fmac_f32_e32 v138, v137, v135
	v_fma_f32 v134, -v134, v138, v136
	v_div_fmas_f32 v134, v134, v135, v138
	v_div_fixup_f32 v134, v134, v133, v33
	v_mul_f32_e32 v134, v41, v134
	v_med3_f32 v134, v134, s57, v194
	v_cvt_f16_f32_e32 v139, v134
	v_mul_f32_e32 v132, 0xbfb8aa3b, v37
	v_exp_f32_e32 v132, v132
	s_nop 0
	v_add_f32_e32 v133, 1.0, v132
	v_div_scale_f32 v134, s[8:9], v133, v133, v37
	v_rcp_f32_e32 v135, v134
	v_div_scale_f32 v136, vcc, v37, v133, v37
	v_fma_f32 v137, -v134, v135, 1.0
	v_fmac_f32_e32 v135, v137, v135
	v_mul_f32_e32 v138, v136, v135
	v_fma_f32 v137, -v134, v138, v136
	v_fmac_f32_e32 v138, v137, v135
	v_fma_f32 v134, -v134, v138, v136
	v_div_fmas_f32 v134, v134, v135, v138
	v_div_fixup_f32 v134, v134, v133, v37
	v_mul_f32_e32 v134, v45, v134
	v_med3_f32 v134, v134, s57, v194
	v_cvt_f16_f32_e32 v140, v134
	global_store_short v246, v139, s[100:101]
	global_store_short v246, v140, s[100:101] offset:32
	s_add_u32 s100, s98, 0x2ec00
	s_addc_u32 s101, s99, 0
	v_mul_f32_e32 v132, 0xbfb8aa3b, v34
	v_exp_f32_e32 v132, v132
	s_nop 0
	v_add_f32_e32 v133, 1.0, v132
	v_div_scale_f32 v134, s[8:9], v133, v133, v34
	v_rcp_f32_e32 v135, v134
	v_div_scale_f32 v136, vcc, v34, v133, v34
	v_fma_f32 v137, -v134, v135, 1.0
	v_fmac_f32_e32 v135, v137, v135
	v_mul_f32_e32 v138, v136, v135
	v_fma_f32 v137, -v134, v138, v136
	v_fmac_f32_e32 v138, v137, v135
	v_fma_f32 v134, -v134, v138, v136
	v_div_fmas_f32 v134, v134, v135, v138
	v_div_fixup_f32 v134, v134, v133, v34
	v_mul_f32_e32 v134, v42, v134
	v_med3_f32 v134, v134, s57, v194
	v_cvt_f16_f32_e32 v139, v134
	v_mul_f32_e32 v132, 0xbfb8aa3b, v38
	v_exp_f32_e32 v132, v132
	s_nop 0
	v_add_f32_e32 v133, 1.0, v132
	v_div_scale_f32 v134, s[8:9], v133, v133, v38
	v_rcp_f32_e32 v135, v134
	v_div_scale_f32 v136, vcc, v38, v133, v38
	v_fma_f32 v137, -v134, v135, 1.0
	v_fmac_f32_e32 v135, v137, v135
	v_mul_f32_e32 v138, v136, v135
	v_fma_f32 v137, -v134, v138, v136
	v_fmac_f32_e32 v138, v137, v135
	v_fma_f32 v134, -v134, v138, v136
	v_div_fmas_f32 v134, v134, v135, v138
	v_div_fixup_f32 v134, v134, v133, v38
	v_mul_f32_e32 v134, v46, v134
	v_med3_f32 v134, v134, s57, v194
	v_cvt_f16_f32_e32 v140, v134
	global_store_short v246, v139, s[100:101]
	global_store_short v246, v140, s[100:101] offset:32
	s_add_u32 s100, s98, 0x30200
	s_addc_u32 s101, s99, 0
	v_mul_f32_e32 v132, 0xbfb8aa3b, v35
	v_exp_f32_e32 v132, v132
	s_nop 0
	v_add_f32_e32 v133, 1.0, v132
	v_div_scale_f32 v134, s[8:9], v133, v133, v35
	v_rcp_f32_e32 v135, v134
	v_div_scale_f32 v136, vcc, v35, v133, v35
	v_fma_f32 v137, -v134, v135, 1.0
	v_fmac_f32_e32 v135, v137, v135
	v_mul_f32_e32 v138, v136, v135
	v_fma_f32 v137, -v134, v138, v136
	v_fmac_f32_e32 v138, v137, v135
	v_fma_f32 v134, -v134, v138, v136
	v_div_fmas_f32 v134, v134, v135, v138
	v_div_fixup_f32 v134, v134, v133, v35
	v_mul_f32_e32 v134, v43, v134
	v_med3_f32 v134, v134, s57, v194
	v_cvt_f16_f32_e32 v139, v134
	v_mul_f32_e32 v132, 0xbfb8aa3b, v39
	v_exp_f32_e32 v132, v132
	s_nop 0
	v_add_f32_e32 v133, 1.0, v132
	v_div_scale_f32 v134, s[8:9], v133, v133, v39
	v_rcp_f32_e32 v135, v134
	v_div_scale_f32 v136, vcc, v39, v133, v39
	v_fma_f32 v137, -v134, v135, 1.0
	v_fmac_f32_e32 v135, v137, v135
	v_mul_f32_e32 v138, v136, v135
	v_fma_f32 v137, -v134, v138, v136
	v_fmac_f32_e32 v138, v137, v135
	v_fma_f32 v134, -v134, v138, v136
	v_div_fmas_f32 v134, v134, v135, v138
	v_div_fixup_f32 v134, v134, v133, v39
	v_mul_f32_e32 v134, v47, v134
	v_med3_f32 v134, v134, s57, v194
	v_cvt_f16_f32_e32 v140, v134
	global_store_short v246, v139, s[100:101]
	global_store_short v246, v140, s[100:101] offset:32
	s_add_u32 s100, s98, 0x42000
	s_addc_u32 s101, s99, 0
	v_mul_f32_e32 v132, 0xbfb8aa3b, v48
	v_exp_f32_e32 v132, v132
	s_nop 0
	v_add_f32_e32 v133, 1.0, v132
	v_div_scale_f32 v134, s[8:9], v133, v133, v48
	v_rcp_f32_e32 v135, v134
	v_div_scale_f32 v136, vcc, v48, v133, v48
	v_fma_f32 v137, -v134, v135, 1.0
	v_fmac_f32_e32 v135, v137, v135
	v_mul_f32_e32 v138, v136, v135
	v_fma_f32 v137, -v134, v138, v136
	v_fmac_f32_e32 v138, v137, v135
	v_fma_f32 v134, -v134, v138, v136
	v_div_fmas_f32 v134, v134, v135, v138
	v_div_fixup_f32 v134, v134, v133, v48
	v_mul_f32_e32 v134, v56, v134
	v_med3_f32 v134, v134, s57, v194
	v_cvt_f16_f32_e32 v139, v134
	v_mul_f32_e32 v132, 0xbfb8aa3b, v52
	v_exp_f32_e32 v132, v132
	s_nop 0
	v_add_f32_e32 v133, 1.0, v132
	v_div_scale_f32 v134, s[8:9], v133, v133, v52
	v_rcp_f32_e32 v135, v134
	v_div_scale_f32 v136, vcc, v52, v133, v52
	v_fma_f32 v137, -v134, v135, 1.0
	v_fmac_f32_e32 v135, v137, v135
	v_mul_f32_e32 v138, v136, v135
	v_fma_f32 v137, -v134, v138, v136
	v_fmac_f32_e32 v138, v137, v135
	v_fma_f32 v134, -v134, v138, v136
	v_div_fmas_f32 v134, v134, v135, v138
	v_div_fixup_f32 v134, v134, v133, v52
	v_mul_f32_e32 v134, v60, v134
	v_med3_f32 v134, v134, s57, v194
	v_cvt_f16_f32_e32 v140, v134
	global_store_short v246, v139, s[100:101]
	global_store_short v246, v140, s[100:101] offset:32
	s_add_u32 s100, s98, 0x43600
	s_addc_u32 s101, s99, 0
	v_mul_f32_e32 v132, 0xbfb8aa3b, v49
	v_exp_f32_e32 v132, v132
	s_nop 0
	v_add_f32_e32 v133, 1.0, v132
	v_div_scale_f32 v134, s[8:9], v133, v133, v49
	v_rcp_f32_e32 v135, v134
	v_div_scale_f32 v136, vcc, v49, v133, v49
	v_fma_f32 v137, -v134, v135, 1.0
	v_fmac_f32_e32 v135, v137, v135
	v_mul_f32_e32 v138, v136, v135
	v_fma_f32 v137, -v134, v138, v136
	v_fmac_f32_e32 v138, v137, v135
	v_fma_f32 v134, -v134, v138, v136
	v_div_fmas_f32 v134, v134, v135, v138
	v_div_fixup_f32 v134, v134, v133, v49
	v_mul_f32_e32 v134, v57, v134
	v_med3_f32 v134, v134, s57, v194
	v_cvt_f16_f32_e32 v139, v134
	v_mul_f32_e32 v132, 0xbfb8aa3b, v53
	v_exp_f32_e32 v132, v132
	s_nop 0
	v_add_f32_e32 v133, 1.0, v132
	v_div_scale_f32 v134, s[8:9], v133, v133, v53
	v_rcp_f32_e32 v135, v134
	v_div_scale_f32 v136, vcc, v53, v133, v53
	v_fma_f32 v137, -v134, v135, 1.0
	v_fmac_f32_e32 v135, v137, v135
	v_mul_f32_e32 v138, v136, v135
	v_fma_f32 v137, -v134, v138, v136
	v_fmac_f32_e32 v138, v137, v135
	v_fma_f32 v134, -v134, v138, v136
	v_div_fmas_f32 v134, v134, v135, v138
	v_div_fixup_f32 v134, v134, v133, v53
	v_mul_f32_e32 v134, v61, v134
	v_med3_f32 v134, v134, s57, v194
	v_cvt_f16_f32_e32 v140, v134
	global_store_short v246, v139, s[100:101]
	global_store_short v246, v140, s[100:101] offset:32
	s_add_u32 s100, s98, 0x44c00
	s_addc_u32 s101, s99, 0
	v_mul_f32_e32 v132, 0xbfb8aa3b, v50
	v_exp_f32_e32 v132, v132
	s_nop 0
	v_add_f32_e32 v133, 1.0, v132
	v_div_scale_f32 v134, s[8:9], v133, v133, v50
	v_rcp_f32_e32 v135, v134
	v_div_scale_f32 v136, vcc, v50, v133, v50
	v_fma_f32 v137, -v134, v135, 1.0
	v_fmac_f32_e32 v135, v137, v135
	v_mul_f32_e32 v138, v136, v135
	v_fma_f32 v137, -v134, v138, v136
	v_fmac_f32_e32 v138, v137, v135
	v_fma_f32 v134, -v134, v138, v136
	v_div_fmas_f32 v134, v134, v135, v138
	v_div_fixup_f32 v134, v134, v133, v50
	v_mul_f32_e32 v134, v58, v134
	v_med3_f32 v134, v134, s57, v194
	v_cvt_f16_f32_e32 v139, v134
	v_mul_f32_e32 v132, 0xbfb8aa3b, v54
	v_exp_f32_e32 v132, v132
	s_nop 0
	v_add_f32_e32 v133, 1.0, v132
	v_div_scale_f32 v134, s[8:9], v133, v133, v54
	v_rcp_f32_e32 v135, v134
	v_div_scale_f32 v136, vcc, v54, v133, v54
	v_fma_f32 v137, -v134, v135, 1.0
	v_fmac_f32_e32 v135, v137, v135
	v_mul_f32_e32 v138, v136, v135
	v_fma_f32 v137, -v134, v138, v136
	v_fmac_f32_e32 v138, v137, v135
	v_fma_f32 v134, -v134, v138, v136
	v_div_fmas_f32 v134, v134, v135, v138
	v_div_fixup_f32 v134, v134, v133, v54
	v_mul_f32_e32 v134, v62, v134
	v_med3_f32 v134, v134, s57, v194
	v_cvt_f16_f32_e32 v140, v134
	global_store_short v246, v139, s[100:101]
	global_store_short v246, v140, s[100:101] offset:32
	s_add_u32 s100, s98, 0x46200
	s_addc_u32 s101, s99, 0
	v_mul_f32_e32 v132, 0xbfb8aa3b, v51
	v_exp_f32_e32 v132, v132
	s_nop 0
	v_add_f32_e32 v133, 1.0, v132
	v_div_scale_f32 v134, s[8:9], v133, v133, v51
	v_rcp_f32_e32 v135, v134
	v_div_scale_f32 v136, vcc, v51, v133, v51
	v_fma_f32 v137, -v134, v135, 1.0
	v_fmac_f32_e32 v135, v137, v135
	v_mul_f32_e32 v138, v136, v135
	v_fma_f32 v137, -v134, v138, v136
	v_fmac_f32_e32 v138, v137, v135
	v_fma_f32 v134, -v134, v138, v136
	v_div_fmas_f32 v134, v134, v135, v138
	v_div_fixup_f32 v134, v134, v133, v51
	v_mul_f32_e32 v134, v59, v134
	v_med3_f32 v134, v134, s57, v194
	v_cvt_f16_f32_e32 v139, v134
	v_mul_f32_e32 v132, 0xbfb8aa3b, v55
	v_exp_f32_e32 v132, v132
	s_nop 0
	v_add_f32_e32 v133, 1.0, v132
	v_div_scale_f32 v134, s[8:9], v133, v133, v55
	v_rcp_f32_e32 v135, v134
	v_div_scale_f32 v136, vcc, v55, v133, v55
	v_fma_f32 v137, -v134, v135, 1.0
	v_fmac_f32_e32 v135, v137, v135
	v_mul_f32_e32 v138, v136, v135
	v_fma_f32 v137, -v134, v138, v136
	v_fmac_f32_e32 v138, v137, v135
	v_fma_f32 v134, -v134, v138, v136
	v_div_fmas_f32 v134, v134, v135, v138
	v_div_fixup_f32 v134, v134, v133, v55
	v_mul_f32_e32 v134, v63, v134
	v_med3_f32 v134, v134, s57, v194
	v_cvt_f16_f32_e32 v140, v134
	global_store_short v246, v139, s[100:101]
	global_store_short v246, v140, s[100:101] offset:32
	s_add_u32 s100, s98, 0x58000
	s_addc_u32 s101, s99, 0
	v_mul_f32_e32 v132, 0xbfb8aa3b, v64
	v_exp_f32_e32 v132, v132
	s_nop 0
	v_add_f32_e32 v133, 1.0, v132
	v_div_scale_f32 v134, s[8:9], v133, v133, v64
	v_rcp_f32_e32 v135, v134
	v_div_scale_f32 v136, vcc, v64, v133, v64
	v_fma_f32 v137, -v134, v135, 1.0
	v_fmac_f32_e32 v135, v137, v135
	v_mul_f32_e32 v138, v136, v135
	v_fma_f32 v137, -v134, v138, v136
	v_fmac_f32_e32 v138, v137, v135
	v_fma_f32 v134, -v134, v138, v136
	v_div_fmas_f32 v134, v134, v135, v138
	v_div_fixup_f32 v134, v134, v133, v64
	v_mul_f32_e32 v134, v72, v134
	v_med3_f32 v134, v134, s57, v194
	v_cvt_f16_f32_e32 v139, v134
	v_mul_f32_e32 v132, 0xbfb8aa3b, v68
	v_exp_f32_e32 v132, v132
	s_nop 0
	v_add_f32_e32 v133, 1.0, v132
	v_div_scale_f32 v134, s[8:9], v133, v133, v68
	v_rcp_f32_e32 v135, v134
	v_div_scale_f32 v136, vcc, v68, v133, v68
	v_fma_f32 v137, -v134, v135, 1.0
	v_fmac_f32_e32 v135, v137, v135
	v_mul_f32_e32 v138, v136, v135
	v_fma_f32 v137, -v134, v138, v136
	v_fmac_f32_e32 v138, v137, v135
	v_fma_f32 v134, -v134, v138, v136
	v_div_fmas_f32 v134, v134, v135, v138
	v_div_fixup_f32 v134, v134, v133, v68
	v_mul_f32_e32 v134, v76, v134
	v_med3_f32 v134, v134, s57, v194
	v_cvt_f16_f32_e32 v140, v134
	global_store_short v246, v139, s[100:101]
	global_store_short v246, v140, s[100:101] offset:32
	s_add_u32 s100, s98, 0x59600
	s_addc_u32 s101, s99, 0
	v_mul_f32_e32 v132, 0xbfb8aa3b, v65
	v_exp_f32_e32 v132, v132
	s_nop 0
	v_add_f32_e32 v133, 1.0, v132
	v_div_scale_f32 v134, s[8:9], v133, v133, v65
	v_rcp_f32_e32 v135, v134
	v_div_scale_f32 v136, vcc, v65, v133, v65
	v_fma_f32 v137, -v134, v135, 1.0
	v_fmac_f32_e32 v135, v137, v135
	v_mul_f32_e32 v138, v136, v135
	v_fma_f32 v137, -v134, v138, v136
	v_fmac_f32_e32 v138, v137, v135
	v_fma_f32 v134, -v134, v138, v136
	v_div_fmas_f32 v134, v134, v135, v138
	v_div_fixup_f32 v134, v134, v133, v65
	v_mul_f32_e32 v134, v73, v134
	v_med3_f32 v134, v134, s57, v194
	v_cvt_f16_f32_e32 v139, v134
	v_mul_f32_e32 v132, 0xbfb8aa3b, v69
	v_exp_f32_e32 v132, v132
	s_nop 0
	v_add_f32_e32 v133, 1.0, v132
	v_div_scale_f32 v134, s[8:9], v133, v133, v69
	v_rcp_f32_e32 v135, v134
	v_div_scale_f32 v136, vcc, v69, v133, v69
	v_fma_f32 v137, -v134, v135, 1.0
	v_fmac_f32_e32 v135, v137, v135
	v_mul_f32_e32 v138, v136, v135
	v_fma_f32 v137, -v134, v138, v136
	v_fmac_f32_e32 v138, v137, v135
	v_fma_f32 v134, -v134, v138, v136
	v_div_fmas_f32 v134, v134, v135, v138
	v_div_fixup_f32 v134, v134, v133, v69
	v_mul_f32_e32 v134, v77, v134
	v_med3_f32 v134, v134, s57, v194
	v_cvt_f16_f32_e32 v140, v134
	global_store_short v246, v139, s[100:101]
	global_store_short v246, v140, s[100:101] offset:32
	s_add_u32 s100, s98, 0x5ac00
	s_addc_u32 s101, s99, 0
	v_mul_f32_e32 v132, 0xbfb8aa3b, v66
	v_exp_f32_e32 v132, v132
	s_nop 0
	v_add_f32_e32 v133, 1.0, v132
	v_div_scale_f32 v134, s[8:9], v133, v133, v66
	v_rcp_f32_e32 v135, v134
	v_div_scale_f32 v136, vcc, v66, v133, v66
	v_fma_f32 v137, -v134, v135, 1.0
	v_fmac_f32_e32 v135, v137, v135
	v_mul_f32_e32 v138, v136, v135
	v_fma_f32 v137, -v134, v138, v136
	v_fmac_f32_e32 v138, v137, v135
	v_fma_f32 v134, -v134, v138, v136
	v_div_fmas_f32 v134, v134, v135, v138
	v_div_fixup_f32 v134, v134, v133, v66
	v_mul_f32_e32 v134, v74, v134
	v_med3_f32 v134, v134, s57, v194
	v_cvt_f16_f32_e32 v139, v134
	v_mul_f32_e32 v132, 0xbfb8aa3b, v70
	v_exp_f32_e32 v132, v132
	s_nop 0
	v_add_f32_e32 v133, 1.0, v132
	v_div_scale_f32 v134, s[8:9], v133, v133, v70
	v_rcp_f32_e32 v135, v134
	v_div_scale_f32 v136, vcc, v70, v133, v70
	v_fma_f32 v137, -v134, v135, 1.0
	v_fmac_f32_e32 v135, v137, v135
	v_mul_f32_e32 v138, v136, v135
	v_fma_f32 v137, -v134, v138, v136
	v_fmac_f32_e32 v138, v137, v135
	v_fma_f32 v134, -v134, v138, v136
	v_div_fmas_f32 v134, v134, v135, v138
	v_div_fixup_f32 v134, v134, v133, v70
	v_mul_f32_e32 v134, v78, v134
	v_med3_f32 v134, v134, s57, v194
	v_cvt_f16_f32_e32 v140, v134
	global_store_short v246, v139, s[100:101]
	global_store_short v246, v140, s[100:101] offset:32
	s_add_u32 s100, s98, 0x5c200
	s_addc_u32 s101, s99, 0
	v_mul_f32_e32 v132, 0xbfb8aa3b, v67
	v_exp_f32_e32 v132, v132
	s_nop 0
	v_add_f32_e32 v133, 1.0, v132
	v_div_scale_f32 v134, s[8:9], v133, v133, v67
	v_rcp_f32_e32 v135, v134
	v_div_scale_f32 v136, vcc, v67, v133, v67
	v_fma_f32 v137, -v134, v135, 1.0
	v_fmac_f32_e32 v135, v137, v135
	v_mul_f32_e32 v138, v136, v135
	v_fma_f32 v137, -v134, v138, v136
	v_fmac_f32_e32 v138, v137, v135
	v_fma_f32 v134, -v134, v138, v136
	v_div_fmas_f32 v134, v134, v135, v138
	v_div_fixup_f32 v134, v134, v133, v67
	v_mul_f32_e32 v134, v75, v134
	v_med3_f32 v134, v134, s57, v194
	v_cvt_f16_f32_e32 v139, v134
	v_mul_f32_e32 v132, 0xbfb8aa3b, v71
	v_exp_f32_e32 v132, v132
	s_nop 0
	v_add_f32_e32 v133, 1.0, v132
	v_div_scale_f32 v134, s[8:9], v133, v133, v71
	v_rcp_f32_e32 v135, v134
	v_div_scale_f32 v136, vcc, v71, v133, v71
	v_fma_f32 v137, -v134, v135, 1.0
	v_fmac_f32_e32 v135, v137, v135
	v_mul_f32_e32 v138, v136, v135
	v_fma_f32 v137, -v134, v138, v136
	v_fmac_f32_e32 v138, v137, v135
	v_fma_f32 v134, -v134, v138, v136
	v_div_fmas_f32 v134, v134, v135, v138
	v_div_fixup_f32 v134, v134, v133, v71
	v_mul_f32_e32 v134, v79, v134
	v_med3_f32 v134, v134, s57, v194
	v_cvt_f16_f32_e32 v140, v134
	global_store_short v246, v139, s[100:101]
	global_store_short v246, v140, s[100:101] offset:32
	s_add_u32 s100, s98, 0x6e000
	s_addc_u32 s101, s99, 0
	v_mul_f32_e32 v132, 0xbfb8aa3b, v80
	v_exp_f32_e32 v132, v132
	s_nop 0
	v_add_f32_e32 v133, 1.0, v132
	v_div_scale_f32 v134, s[8:9], v133, v133, v80
	v_rcp_f32_e32 v135, v134
	v_div_scale_f32 v136, vcc, v80, v133, v80
	v_fma_f32 v137, -v134, v135, 1.0
	v_fmac_f32_e32 v135, v137, v135
	v_mul_f32_e32 v138, v136, v135
	v_fma_f32 v137, -v134, v138, v136
	v_fmac_f32_e32 v138, v137, v135
	v_fma_f32 v134, -v134, v138, v136
	v_div_fmas_f32 v134, v134, v135, v138
	v_div_fixup_f32 v134, v134, v133, v80
	v_mul_f32_e32 v134, v88, v134
	v_med3_f32 v134, v134, s57, v194
	v_cvt_f16_f32_e32 v139, v134
	v_mul_f32_e32 v132, 0xbfb8aa3b, v84
	v_exp_f32_e32 v132, v132
	s_nop 0
	v_add_f32_e32 v133, 1.0, v132
	v_div_scale_f32 v134, s[8:9], v133, v133, v84
	v_rcp_f32_e32 v135, v134
	v_div_scale_f32 v136, vcc, v84, v133, v84
	v_fma_f32 v137, -v134, v135, 1.0
	v_fmac_f32_e32 v135, v137, v135
	v_mul_f32_e32 v138, v136, v135
	v_fma_f32 v137, -v134, v138, v136
	v_fmac_f32_e32 v138, v137, v135
	v_fma_f32 v134, -v134, v138, v136
	v_div_fmas_f32 v134, v134, v135, v138
	v_div_fixup_f32 v134, v134, v133, v84
	v_mul_f32_e32 v134, v92, v134
	v_med3_f32 v134, v134, s57, v194
	v_cvt_f16_f32_e32 v140, v134
	global_store_short v246, v139, s[100:101]
	global_store_short v246, v140, s[100:101] offset:32
	s_add_u32 s100, s98, 0x6f600
	s_addc_u32 s101, s99, 0
	v_mul_f32_e32 v132, 0xbfb8aa3b, v81
	v_exp_f32_e32 v132, v132
	s_nop 0
	v_add_f32_e32 v133, 1.0, v132
	v_div_scale_f32 v134, s[8:9], v133, v133, v81
	v_rcp_f32_e32 v135, v134
	v_div_scale_f32 v136, vcc, v81, v133, v81
	v_fma_f32 v137, -v134, v135, 1.0
	v_fmac_f32_e32 v135, v137, v135
	v_mul_f32_e32 v138, v136, v135
	v_fma_f32 v137, -v134, v138, v136
	v_fmac_f32_e32 v138, v137, v135
	v_fma_f32 v134, -v134, v138, v136
	v_div_fmas_f32 v134, v134, v135, v138
	v_div_fixup_f32 v134, v134, v133, v81
	v_mul_f32_e32 v134, v89, v134
	v_med3_f32 v134, v134, s57, v194
	v_cvt_f16_f32_e32 v139, v134
	v_mul_f32_e32 v132, 0xbfb8aa3b, v85
	v_exp_f32_e32 v132, v132
	s_nop 0
	v_add_f32_e32 v133, 1.0, v132
	v_div_scale_f32 v134, s[8:9], v133, v133, v85
	v_rcp_f32_e32 v135, v134
	v_div_scale_f32 v136, vcc, v85, v133, v85
	v_fma_f32 v137, -v134, v135, 1.0
	v_fmac_f32_e32 v135, v137, v135
	v_mul_f32_e32 v138, v136, v135
	v_fma_f32 v137, -v134, v138, v136
	v_fmac_f32_e32 v138, v137, v135
	v_fma_f32 v134, -v134, v138, v136
	v_div_fmas_f32 v134, v134, v135, v138
	v_div_fixup_f32 v134, v134, v133, v85
	v_mul_f32_e32 v134, v93, v134
	v_med3_f32 v134, v134, s57, v194
	v_cvt_f16_f32_e32 v140, v134
	global_store_short v246, v139, s[100:101]
	global_store_short v246, v140, s[100:101] offset:32
	s_add_u32 s100, s98, 0x70c00
	s_addc_u32 s101, s99, 0
	v_mul_f32_e32 v132, 0xbfb8aa3b, v82
	v_exp_f32_e32 v132, v132
	s_nop 0
	v_add_f32_e32 v133, 1.0, v132
	v_div_scale_f32 v134, s[8:9], v133, v133, v82
	v_rcp_f32_e32 v135, v134
	v_div_scale_f32 v136, vcc, v82, v133, v82
	v_fma_f32 v137, -v134, v135, 1.0
	v_fmac_f32_e32 v135, v137, v135
	v_mul_f32_e32 v138, v136, v135
	v_fma_f32 v137, -v134, v138, v136
	v_fmac_f32_e32 v138, v137, v135
	v_fma_f32 v134, -v134, v138, v136
	v_div_fmas_f32 v134, v134, v135, v138
	v_div_fixup_f32 v134, v134, v133, v82
	v_mul_f32_e32 v134, v90, v134
	v_med3_f32 v134, v134, s57, v194
	v_cvt_f16_f32_e32 v139, v134
	v_mul_f32_e32 v132, 0xbfb8aa3b, v86
	v_exp_f32_e32 v132, v132
	s_nop 0
	v_add_f32_e32 v133, 1.0, v132
	v_div_scale_f32 v134, s[8:9], v133, v133, v86
	v_rcp_f32_e32 v135, v134
	v_div_scale_f32 v136, vcc, v86, v133, v86
	v_fma_f32 v137, -v134, v135, 1.0
	v_fmac_f32_e32 v135, v137, v135
	v_mul_f32_e32 v138, v136, v135
	v_fma_f32 v137, -v134, v138, v136
	v_fmac_f32_e32 v138, v137, v135
	v_fma_f32 v134, -v134, v138, v136
	v_div_fmas_f32 v134, v134, v135, v138
	v_div_fixup_f32 v134, v134, v133, v86
	v_mul_f32_e32 v134, v94, v134
	v_med3_f32 v134, v134, s57, v194
	v_cvt_f16_f32_e32 v140, v134
	global_store_short v246, v139, s[100:101]
	global_store_short v246, v140, s[100:101] offset:32
	s_add_u32 s100, s98, 0x72200
	s_addc_u32 s101, s99, 0
	v_mul_f32_e32 v132, 0xbfb8aa3b, v83
	v_exp_f32_e32 v132, v132
	s_nop 0
	v_add_f32_e32 v133, 1.0, v132
	v_div_scale_f32 v134, s[8:9], v133, v133, v83
	v_rcp_f32_e32 v135, v134
	v_div_scale_f32 v136, vcc, v83, v133, v83
	v_fma_f32 v137, -v134, v135, 1.0
	v_fmac_f32_e32 v135, v137, v135
	v_mul_f32_e32 v138, v136, v135
	v_fma_f32 v137, -v134, v138, v136
	v_fmac_f32_e32 v138, v137, v135
	v_fma_f32 v134, -v134, v138, v136
	v_div_fmas_f32 v134, v134, v135, v138
	v_div_fixup_f32 v134, v134, v133, v83
	v_mul_f32_e32 v134, v91, v134
	v_med3_f32 v134, v134, s57, v194
	v_cvt_f16_f32_e32 v139, v134
	v_mul_f32_e32 v132, 0xbfb8aa3b, v87
	v_exp_f32_e32 v132, v132
	s_nop 0
	v_add_f32_e32 v133, 1.0, v132
	v_div_scale_f32 v134, s[8:9], v133, v133, v87
	v_rcp_f32_e32 v135, v134
	v_div_scale_f32 v136, vcc, v87, v133, v87
	v_fma_f32 v137, -v134, v135, 1.0
	v_fmac_f32_e32 v135, v137, v135
	v_mul_f32_e32 v138, v136, v135
	v_fma_f32 v137, -v134, v138, v136
	v_fmac_f32_e32 v138, v137, v135
	v_fma_f32 v134, -v134, v138, v136
	v_div_fmas_f32 v134, v134, v135, v138
	v_div_fixup_f32 v134, v134, v133, v87
	v_mul_f32_e32 v134, v95, v134
	v_med3_f32 v134, v134, s57, v194
	v_cvt_f16_f32_e32 v140, v134
	global_store_short v246, v139, s[100:101]
	global_store_short v246, v140, s[100:101] offset:32
	s_add_u32 s100, s98, 0x84000
	s_addc_u32 s101, s99, 0
	v_mul_f32_e32 v132, 0xbfb8aa3b, v96
	v_exp_f32_e32 v132, v132
	s_nop 0
	v_add_f32_e32 v133, 1.0, v132
	v_div_scale_f32 v134, s[8:9], v133, v133, v96
	v_rcp_f32_e32 v135, v134
	v_div_scale_f32 v136, vcc, v96, v133, v96
	v_fma_f32 v137, -v134, v135, 1.0
	v_fmac_f32_e32 v135, v137, v135
	v_mul_f32_e32 v138, v136, v135
	v_fma_f32 v137, -v134, v138, v136
	v_fmac_f32_e32 v138, v137, v135
	v_fma_f32 v134, -v134, v138, v136
	v_div_fmas_f32 v134, v134, v135, v138
	v_div_fixup_f32 v134, v134, v133, v96
	v_mul_f32_e32 v134, v104, v134
	v_med3_f32 v134, v134, s57, v194
	v_cvt_f16_f32_e32 v139, v134
	v_mul_f32_e32 v132, 0xbfb8aa3b, v100
	v_exp_f32_e32 v132, v132
	s_nop 0
	v_add_f32_e32 v133, 1.0, v132
	v_div_scale_f32 v134, s[8:9], v133, v133, v100
	v_rcp_f32_e32 v135, v134
	v_div_scale_f32 v136, vcc, v100, v133, v100
	v_fma_f32 v137, -v134, v135, 1.0
	v_fmac_f32_e32 v135, v137, v135
	v_mul_f32_e32 v138, v136, v135
	v_fma_f32 v137, -v134, v138, v136
	v_fmac_f32_e32 v138, v137, v135
	v_fma_f32 v134, -v134, v138, v136
	v_div_fmas_f32 v134, v134, v135, v138
	v_div_fixup_f32 v134, v134, v133, v100
	v_mul_f32_e32 v134, v108, v134
	v_med3_f32 v134, v134, s57, v194
	v_cvt_f16_f32_e32 v140, v134
	global_store_short v246, v139, s[100:101]
	global_store_short v246, v140, s[100:101] offset:32
	s_add_u32 s100, s98, 0x85600
	s_addc_u32 s101, s99, 0
	v_mul_f32_e32 v132, 0xbfb8aa3b, v97
	v_exp_f32_e32 v132, v132
	s_nop 0
	v_add_f32_e32 v133, 1.0, v132
	v_div_scale_f32 v134, s[8:9], v133, v133, v97
	v_rcp_f32_e32 v135, v134
	v_div_scale_f32 v136, vcc, v97, v133, v97
	v_fma_f32 v137, -v134, v135, 1.0
	v_fmac_f32_e32 v135, v137, v135
	v_mul_f32_e32 v138, v136, v135
	v_fma_f32 v137, -v134, v138, v136
	v_fmac_f32_e32 v138, v137, v135
	v_fma_f32 v134, -v134, v138, v136
	v_div_fmas_f32 v134, v134, v135, v138
	v_div_fixup_f32 v134, v134, v133, v97
	v_mul_f32_e32 v134, v105, v134
	v_med3_f32 v134, v134, s57, v194
	v_cvt_f16_f32_e32 v139, v134
	v_mul_f32_e32 v132, 0xbfb8aa3b, v101
	v_exp_f32_e32 v132, v132
	s_nop 0
	v_add_f32_e32 v133, 1.0, v132
	v_div_scale_f32 v134, s[8:9], v133, v133, v101
	v_rcp_f32_e32 v135, v134
	v_div_scale_f32 v136, vcc, v101, v133, v101
	v_fma_f32 v137, -v134, v135, 1.0
	v_fmac_f32_e32 v135, v137, v135
	v_mul_f32_e32 v138, v136, v135
	v_fma_f32 v137, -v134, v138, v136
	v_fmac_f32_e32 v138, v137, v135
	v_fma_f32 v134, -v134, v138, v136
	v_div_fmas_f32 v134, v134, v135, v138
	v_div_fixup_f32 v134, v134, v133, v101
	v_mul_f32_e32 v134, v109, v134
	v_med3_f32 v134, v134, s57, v194
	v_cvt_f16_f32_e32 v140, v134
	global_store_short v246, v139, s[100:101]
	global_store_short v246, v140, s[100:101] offset:32
	s_add_u32 s100, s98, 0x86c00
	s_addc_u32 s101, s99, 0
	v_mul_f32_e32 v132, 0xbfb8aa3b, v98
	v_exp_f32_e32 v132, v132
	s_nop 0
	v_add_f32_e32 v133, 1.0, v132
	v_div_scale_f32 v134, s[8:9], v133, v133, v98
	v_rcp_f32_e32 v135, v134
	v_div_scale_f32 v136, vcc, v98, v133, v98
	v_fma_f32 v137, -v134, v135, 1.0
	v_fmac_f32_e32 v135, v137, v135
	v_mul_f32_e32 v138, v136, v135
	v_fma_f32 v137, -v134, v138, v136
	v_fmac_f32_e32 v138, v137, v135
	v_fma_f32 v134, -v134, v138, v136
	v_div_fmas_f32 v134, v134, v135, v138
	v_div_fixup_f32 v134, v134, v133, v98
	v_mul_f32_e32 v134, v106, v134
	v_med3_f32 v134, v134, s57, v194
	v_cvt_f16_f32_e32 v139, v134
	v_mul_f32_e32 v132, 0xbfb8aa3b, v102
	v_exp_f32_e32 v132, v132
	s_nop 0
	v_add_f32_e32 v133, 1.0, v132
	v_div_scale_f32 v134, s[8:9], v133, v133, v102
	v_rcp_f32_e32 v135, v134
	v_div_scale_f32 v136, vcc, v102, v133, v102
	v_fma_f32 v137, -v134, v135, 1.0
	v_fmac_f32_e32 v135, v137, v135
	v_mul_f32_e32 v138, v136, v135
	v_fma_f32 v137, -v134, v138, v136
	v_fmac_f32_e32 v138, v137, v135
	v_fma_f32 v134, -v134, v138, v136
	v_div_fmas_f32 v134, v134, v135, v138
	v_div_fixup_f32 v134, v134, v133, v102
	v_mul_f32_e32 v134, v110, v134
	v_med3_f32 v134, v134, s57, v194
	v_cvt_f16_f32_e32 v140, v134
	global_store_short v246, v139, s[100:101]
	global_store_short v246, v140, s[100:101] offset:32
	s_add_u32 s100, s98, 0x88200
	s_addc_u32 s101, s99, 0
	v_mul_f32_e32 v132, 0xbfb8aa3b, v99
	v_exp_f32_e32 v132, v132
	s_nop 0
	v_add_f32_e32 v133, 1.0, v132
	v_div_scale_f32 v134, s[8:9], v133, v133, v99
	v_rcp_f32_e32 v135, v134
	v_div_scale_f32 v136, vcc, v99, v133, v99
	v_fma_f32 v137, -v134, v135, 1.0
	v_fmac_f32_e32 v135, v137, v135
	v_mul_f32_e32 v138, v136, v135
	v_fma_f32 v137, -v134, v138, v136
	v_fmac_f32_e32 v138, v137, v135
	v_fma_f32 v134, -v134, v138, v136
	v_div_fmas_f32 v134, v134, v135, v138
	v_div_fixup_f32 v134, v134, v133, v99
	v_mul_f32_e32 v134, v107, v134
	v_med3_f32 v134, v134, s57, v194
	v_cvt_f16_f32_e32 v139, v134
	v_mul_f32_e32 v132, 0xbfb8aa3b, v103
	v_exp_f32_e32 v132, v132
	s_nop 0
	v_add_f32_e32 v133, 1.0, v132
	v_div_scale_f32 v134, s[8:9], v133, v133, v103
	v_rcp_f32_e32 v135, v134
	v_div_scale_f32 v136, vcc, v103, v133, v103
	v_fma_f32 v137, -v134, v135, 1.0
	v_fmac_f32_e32 v135, v137, v135
	v_mul_f32_e32 v138, v136, v135
	v_fma_f32 v137, -v134, v138, v136
	v_fmac_f32_e32 v138, v137, v135
	v_fma_f32 v134, -v134, v138, v136
	v_div_fmas_f32 v134, v134, v135, v138
	v_div_fixup_f32 v134, v134, v133, v103
	v_mul_f32_e32 v134, v111, v134
	v_med3_f32 v134, v134, s57, v194
	v_cvt_f16_f32_e32 v140, v134
	global_store_short v246, v139, s[100:101]
	global_store_short v246, v140, s[100:101] offset:32
	s_add_u32 s100, s98, 0x9a000
	s_addc_u32 s101, s99, 0
	v_mul_f32_e32 v132, 0xbfb8aa3b, v116
	v_exp_f32_e32 v132, v132
	s_nop 0
	v_add_f32_e32 v133, 1.0, v132
	v_div_scale_f32 v134, s[8:9], v133, v133, v116
	v_rcp_f32_e32 v135, v134
	v_div_scale_f32 v136, vcc, v116, v133, v116
	v_fma_f32 v137, -v134, v135, 1.0
	v_fmac_f32_e32 v135, v137, v135
	v_mul_f32_e32 v138, v136, v135
	v_fma_f32 v137, -v134, v138, v136
	v_fmac_f32_e32 v138, v137, v135
	v_fma_f32 v134, -v134, v138, v136
	v_div_fmas_f32 v134, v134, v135, v138
	v_div_fixup_f32 v134, v134, v133, v116
	v_mul_f32_e32 v134, v124, v134
	v_med3_f32 v134, v134, s57, v194
	v_cvt_f16_f32_e32 v139, v134
	v_mul_f32_e32 v132, 0xbfb8aa3b, v120
	v_exp_f32_e32 v132, v132
	s_nop 0
	v_add_f32_e32 v133, 1.0, v132
	v_div_scale_f32 v134, s[8:9], v133, v133, v120
	v_rcp_f32_e32 v135, v134
	v_div_scale_f32 v136, vcc, v120, v133, v120
	v_fma_f32 v137, -v134, v135, 1.0
	v_fmac_f32_e32 v135, v137, v135
	v_mul_f32_e32 v138, v136, v135
	v_fma_f32 v137, -v134, v138, v136
	v_fmac_f32_e32 v138, v137, v135
	v_fma_f32 v134, -v134, v138, v136
	v_div_fmas_f32 v134, v134, v135, v138
	v_div_fixup_f32 v134, v134, v133, v120
	v_mul_f32_e32 v134, v128, v134
	v_med3_f32 v134, v134, s57, v194
	v_cvt_f16_f32_e32 v140, v134
	global_store_short v246, v139, s[100:101]
	global_store_short v246, v140, s[100:101] offset:32
	s_add_u32 s100, s98, 0x9b600
	s_addc_u32 s101, s99, 0
	v_mul_f32_e32 v132, 0xbfb8aa3b, v117
	v_exp_f32_e32 v132, v132
	s_nop 0
	v_add_f32_e32 v133, 1.0, v132
	v_div_scale_f32 v134, s[8:9], v133, v133, v117
	v_rcp_f32_e32 v135, v134
	v_div_scale_f32 v136, vcc, v117, v133, v117
	v_fma_f32 v137, -v134, v135, 1.0
	v_fmac_f32_e32 v135, v137, v135
	v_mul_f32_e32 v138, v136, v135
	v_fma_f32 v137, -v134, v138, v136
	v_fmac_f32_e32 v138, v137, v135
	v_fma_f32 v134, -v134, v138, v136
	v_div_fmas_f32 v134, v134, v135, v138
	v_div_fixup_f32 v134, v134, v133, v117
	v_mul_f32_e32 v134, v125, v134
	v_med3_f32 v134, v134, s57, v194
	v_cvt_f16_f32_e32 v139, v134
	v_mul_f32_e32 v132, 0xbfb8aa3b, v121
	v_exp_f32_e32 v132, v132
	s_nop 0
	v_add_f32_e32 v133, 1.0, v132
	v_div_scale_f32 v134, s[8:9], v133, v133, v121
	v_rcp_f32_e32 v135, v134
	v_div_scale_f32 v136, vcc, v121, v133, v121
	v_fma_f32 v137, -v134, v135, 1.0
	v_fmac_f32_e32 v135, v137, v135
	v_mul_f32_e32 v138, v136, v135
	v_fma_f32 v137, -v134, v138, v136
	v_fmac_f32_e32 v138, v137, v135
	v_fma_f32 v134, -v134, v138, v136
	v_div_fmas_f32 v134, v134, v135, v138
	v_div_fixup_f32 v134, v134, v133, v121
	v_mul_f32_e32 v134, v129, v134
	v_med3_f32 v134, v134, s57, v194
	v_cvt_f16_f32_e32 v140, v134
	global_store_short v246, v139, s[100:101]
	global_store_short v246, v140, s[100:101] offset:32
	s_add_u32 s100, s98, 0x9cc00
	s_addc_u32 s101, s99, 0
	v_mul_f32_e32 v132, 0xbfb8aa3b, v118
	v_exp_f32_e32 v132, v132
	s_nop 0
	v_add_f32_e32 v133, 1.0, v132
	v_div_scale_f32 v134, s[8:9], v133, v133, v118
	v_rcp_f32_e32 v135, v134
	v_div_scale_f32 v136, vcc, v118, v133, v118
	v_fma_f32 v137, -v134, v135, 1.0
	v_fmac_f32_e32 v135, v137, v135
	v_mul_f32_e32 v138, v136, v135
	v_fma_f32 v137, -v134, v138, v136
	v_fmac_f32_e32 v138, v137, v135
	v_fma_f32 v134, -v134, v138, v136
	v_div_fmas_f32 v134, v134, v135, v138
	v_div_fixup_f32 v134, v134, v133, v118
	v_mul_f32_e32 v134, v126, v134
	v_med3_f32 v134, v134, s57, v194
	v_cvt_f16_f32_e32 v139, v134
	v_mul_f32_e32 v132, 0xbfb8aa3b, v122
	v_exp_f32_e32 v132, v132
	s_nop 0
	v_add_f32_e32 v133, 1.0, v132
	v_div_scale_f32 v134, s[8:9], v133, v133, v122
	v_rcp_f32_e32 v135, v134
	v_div_scale_f32 v136, vcc, v122, v133, v122
	v_fma_f32 v137, -v134, v135, 1.0
	v_fmac_f32_e32 v135, v137, v135
	v_mul_f32_e32 v138, v136, v135
	v_fma_f32 v137, -v134, v138, v136
	v_fmac_f32_e32 v138, v137, v135
	v_fma_f32 v134, -v134, v138, v136
	v_div_fmas_f32 v134, v134, v135, v138
	v_div_fixup_f32 v134, v134, v133, v122
	v_mul_f32_e32 v134, v130, v134
	v_med3_f32 v134, v134, s57, v194
	v_cvt_f16_f32_e32 v140, v134
	global_store_short v246, v139, s[100:101]
	global_store_short v246, v140, s[100:101] offset:32
	s_add_u32 s100, s98, 0x9e200
	s_addc_u32 s101, s99, 0
	v_mul_f32_e32 v132, 0xbfb8aa3b, v119
	v_exp_f32_e32 v132, v132
	s_nop 0
	v_add_f32_e32 v133, 1.0, v132
	v_div_scale_f32 v134, s[8:9], v133, v133, v119
	v_rcp_f32_e32 v135, v134
	v_div_scale_f32 v136, vcc, v119, v133, v119
	v_fma_f32 v137, -v134, v135, 1.0
	v_fmac_f32_e32 v135, v137, v135
	v_mul_f32_e32 v138, v136, v135
	v_fma_f32 v137, -v134, v138, v136
	v_fmac_f32_e32 v138, v137, v135
	v_fma_f32 v134, -v134, v138, v136
	v_div_fmas_f32 v134, v134, v135, v138
	v_div_fixup_f32 v134, v134, v133, v119
	v_mul_f32_e32 v134, v127, v134
	v_med3_f32 v134, v134, s57, v194
	v_cvt_f16_f32_e32 v139, v134
	v_mul_f32_e32 v132, 0xbfb8aa3b, v123
	v_exp_f32_e32 v132, v132
	s_nop 0
	v_add_f32_e32 v133, 1.0, v132
	v_div_scale_f32 v134, s[8:9], v133, v133, v123
	v_rcp_f32_e32 v135, v134
	v_div_scale_f32 v136, vcc, v123, v133, v123
	v_fma_f32 v137, -v134, v135, 1.0
	v_fmac_f32_e32 v135, v137, v135
	v_mul_f32_e32 v138, v136, v135
	v_fma_f32 v137, -v134, v138, v136
	v_fmac_f32_e32 v138, v137, v135
	v_fma_f32 v134, -v134, v138, v136
	v_div_fmas_f32 v134, v134, v135, v138
	v_div_fixup_f32 v134, v134, v133, v123
	v_mul_f32_e32 v134, v131, v134
	v_med3_f32 v134, v134, s57, v194
	v_cvt_f16_f32_e32 v140, v134
	global_store_short v246, v139, s[100:101]
	global_store_short v246, v140, s[100:101] offset:32
	s_add_i32 s12, s12, s60
	s_lshr_b32 s4, s62, 1
	s_cmp_ge_i32 s12, s4
	s_cbranch_scc0 .LBB0_136
	v_mov_b32_e32 v113, 0
	v_mov_b32_e32 v114, 0x3f317218

.LBB0_634:
	s_waitcnt lgkmcnt(0)
	s_sub_u32 s4, s0, s65
	s_lshl_b32 s4, s4, 8
	s_lshl_b32 s13, s65, 7
	s_add_u32 s12, s4, s13
	v_lshrrev_b32_e32 v132, 4, v182
	v_xor_b32_e32 v132, v132, v182
	v_and_b32_e32 v132, 7, v132
	v_lshlrev_b32_e32 v132, 4, v132
	v_lshrrev_b32_e32 v133, 3, v182
	v_lshrrev_b32_e32 v134, 6, v182
	v_lshl_or_b32 v180, v133, 11, v132
	v_readfirstlane_b32 s5, v134
	v_and_b32_e32 v135, 15, v182
	v_bfe_u32 v136, v182, 4, 2
	v_bfe_u32 v137, v182, 1, 3
	v_xor_b32_e32 v138, v136, v137
	v_or_b32_e32 v139, 4, v136
	v_xor_b32_e32 v139, v139, v137
	v_lshlrev_b32_e32 v138, 4, v138
	v_lshlrev_b32_e32 v139, 4, v139
	v_lshl_or_b32 v138, v135, 7, v138
	v_lshl_or_b32 v139, v135, 7, v139
	v_bfe_u32 v140, v182, 7, 1
	v_bfe_u32 v141, v182, 6, 1
	v_lshl_add_u32 v181, v140, 14, v138
	v_lshl_add_u32 v208, v140, 14, v139
	v_lshl_add_u32 v223, v141, 13, v138
	v_lshl_add_u32 v233, v141, 13, v139
	v_lshlrev_b32_e32 v142, 2, v136
	v_lshl_or_b32 v142, v140, 7, v142
	v_mul_u32_u24_e32 v246, 0x1600, v142
	v_lshl_or_b32 v142, v141, 5, v135
	v_lshl_add_u32 v246, v142, 1, v246
	s_lshl_b32 s5, s5, 10
	s_lshl_b32 s4, s12, 11
	s_add_u32 s2, s40, s4
	s_addc_u32 s3, s41, 0
	s_lshl_b32 s4, s11, 18
	v_readlane_b32 s8, v250, 17
	v_readlane_b32 s9, v250, 18
	s_add_u32 s8, s8, s4
	s_addc_u32 s9, s9, 0
	s_mul_i32 s4, s12, 0x1600
	s_lshl_b32 s13, s11, 7
	s_add_u32 s4, s4, s13
	s_add_u32 s98, s30, s4
	s_addc_u32 s99, s31, 0
	s_mov_b32 s23, 0x8000
	s_add_u32 m0, s5, 0x0
	s_nop 0
	global_load_lds_dwordx4 v180, s[2:3]
	s_add_u32 m0, s5, 0x1000
	s_add_u32 s20, s2, 0x10000
	s_addc_u32 s21, s3, 0
	global_load_lds_dwordx4 v180, s[20:21]
	s_add_u32 m0, s5, 0x2000
	s_add_u32 s20, s2, 0x20000
	s_addc_u32 s21, s3, 0
	global_load_lds_dwordx4 v180, s[20:21]
	s_add_u32 m0, s5, 0x3000
	s_add_u32 s20, s2, 0x30000
	s_addc_u32 s21, s3, 0
	global_load_lds_dwordx4 v180, s[20:21]
	s_add_u32 m0, s5, 0x4000
	s_add_u32 s20, s2, 0x40000
	s_addc_u32 s21, s3, 0
	global_load_lds_dwordx4 v180, s[20:21]
	s_add_u32 m0, s5, 0x5000
	s_add_u32 s20, s2, 0x50000
	s_addc_u32 s21, s3, 0
	global_load_lds_dwordx4 v180, s[20:21]
	s_add_u32 m0, s5, 0x6000
	s_add_u32 s20, s2, 0x60000
	s_addc_u32 s21, s3, 0
	global_load_lds_dwordx4 v180, s[20:21]
	s_add_u32 m0, s5, 0x7000
	s_add_u32 s20, s2, 0x70000
	s_addc_u32 s21, s3, 0
	global_load_lds_dwordx4 v180, s[20:21]
	s_add_u32 s2, s2, 0x80
	s_addc_u32 s3, s3, 0
	s_add_u32 m0, s5, s23
	s_nop 0
	global_load_lds_dwordx4 v180, s[8:9]
	s_add_u32 m0, m0, 0x1000
	s_add_u32 s20, s8, 0x10000
	s_addc_u32 s21, s9, 0
	global_load_lds_dwordx4 v180, s[20:21]
	s_add_u32 m0, m0, 0x1000
	s_add_u32 s20, s8, 0x20000
	s_addc_u32 s21, s9, 0
	global_load_lds_dwordx4 v180, s[20:21]
	s_add_u32 m0, m0, 0x1000
	s_add_u32 s20, s8, 0x30000
	s_addc_u32 s21, s9, 0
	global_load_lds_dwordx4 v180, s[20:21]
	s_add_u32 s8, s8, 0x80
	s_addc_u32 s9, s9, 0
	v_mov_b32_e32 v0, 0
	v_mov_b32_e32 v1, v0
	v_mov_b32_e32 v2, v0
	v_mov_b32_e32 v3, v0
	v_mov_b32_e32 v4, v0
	v_mov_b32_e32 v5, v0
	v_mov_b32_e32 v6, v0
	v_mov_b32_e32 v7, v0
	v_mov_b32_e32 v8, v0
	v_mov_b32_e32 v9, v0
	v_mov_b32_e32 v10, v0
	v_mov_b32_e32 v11, v0
	v_mov_b32_e32 v12, v0
	v_mov_b32_e32 v13, v0
	v_mov_b32_e32 v14, v0
	v_mov_b32_e32 v15, v0
	v_mov_b32_e32 v16, v0
	v_mov_b32_e32 v17, v0
	v_mov_b32_e32 v18, v0
	v_mov_b32_e32 v19, v0
	v_mov_b32_e32 v20, v0
	v_mov_b32_e32 v21, v0
	v_mov_b32_e32 v22, v0
	v_mov_b32_e32 v23, v0
	v_mov_b32_e32 v24, v0
	v_mov_b32_e32 v25, v0
	v_mov_b32_e32 v26, v0
	v_mov_b32_e32 v27, v0
	v_mov_b32_e32 v28, v0
	v_mov_b32_e32 v29, v0
	v_mov_b32_e32 v30, v0
	v_mov_b32_e32 v31, v0
	v_mov_b32_e32 v32, v0
	v_mov_b32_e32 v33, v0
	v_mov_b32_e32 v34, v0
	v_mov_b32_e32 v35, v0
	v_mov_b32_e32 v36, v0
	v_mov_b32_e32 v37, v0
	v_mov_b32_e32 v38, v0
	v_mov_b32_e32 v39, v0
	v_mov_b32_e32 v40, v0
	v_mov_b32_e32 v41, v0
	v_mov_b32_e32 v42, v0
	v_mov_b32_e32 v43, v0
	v_mov_b32_e32 v44, v0
	v_mov_b32_e32 v45, v0
	v_mov_b32_e32 v46, v0
	v_mov_b32_e32 v47, v0
	v_mov_b32_e32 v48, v0
	v_mov_b32_e32 v49, v0
	v_mov_b32_e32 v50, v0
	v_mov_b32_e32 v51, v0
	v_mov_b32_e32 v52, v0
	v_mov_b32_e32 v53, v0
	v_mov_b32_e32 v54, v0
	v_mov_b32_e32 v55, v0
	v_mov_b32_e32 v56, v0
	v_mov_b32_e32 v57, v0
	v_mov_b32_e32 v58, v0
	v_mov_b32_e32 v59, v0
	v_mov_b32_e32 v60, v0
	v_mov_b32_e32 v61, v0
	v_mov_b32_e32 v62, v0
	v_mov_b32_e32 v63, v0
	v_mov_b32_e32 v64, v0
	v_mov_b32_e32 v65, v0
	v_mov_b32_e32 v66, v0
	v_mov_b32_e32 v67, v0
	v_mov_b32_e32 v68, v0
	v_mov_b32_e32 v69, v0
	v_mov_b32_e32 v70, v0
	v_mov_b32_e32 v71, v0
	v_mov_b32_e32 v72, v0
	v_mov_b32_e32 v73, v0
	v_mov_b32_e32 v74, v0
	v_mov_b32_e32 v75, v0
	v_mov_b32_e32 v76, v0
	v_mov_b32_e32 v77, v0
	v_mov_b32_e32 v78, v0
	v_mov_b32_e32 v79, v0
	v_mov_b32_e32 v80, v0
	v_mov_b32_e32 v81, v0
	v_mov_b32_e32 v82, v0
	v_mov_b32_e32 v83, v0
	v_mov_b32_e32 v84, v0
	v_mov_b32_e32 v85, v0
	v_mov_b32_e32 v86, v0
	v_mov_b32_e32 v87, v0
	v_mov_b32_e32 v88, v0
	v_mov_b32_e32 v89, v0
	v_mov_b32_e32 v90, v0
	v_mov_b32_e32 v91, v0
	v_mov_b32_e32 v92, v0
	v_mov_b32_e32 v93, v0
	v_mov_b32_e32 v94, v0
	v_mov_b32_e32 v95, v0
	v_mov_b32_e32 v96, v0
	v_mov_b32_e32 v97, v0
	v_mov_b32_e32 v98, v0
	v_mov_b32_e32 v99, v0
	v_mov_b32_e32 v100, v0
	v_mov_b32_e32 v101, v0
	v_mov_b32_e32 v102, v0
	v_mov_b32_e32 v103, v0
	v_mov_b32_e32 v104, v0
	v_mov_b32_e32 v105, v0
	v_mov_b32_e32 v106, v0
	v_mov_b32_e32 v107, v0
	v_mov_b32_e32 v108, v0
	v_mov_b32_e32 v109, v0
	v_mov_b32_e32 v110, v0
	v_mov_b32_e32 v111, v0
	v_mov_b32_e32 v116, v0
	v_mov_b32_e32 v117, v0
	v_mov_b32_e32 v118, v0
	v_mov_b32_e32 v119, v0
	v_mov_b32_e32 v120, v0
	v_mov_b32_e32 v121, v0
	v_mov_b32_e32 v122, v0
	v_mov_b32_e32 v123, v0
	v_mov_b32_e32 v124, v0
	v_mov_b32_e32 v125, v0
	v_mov_b32_e32 v126, v0
	v_mov_b32_e32 v127, v0
	v_mov_b32_e32 v128, v0
	v_mov_b32_e32 v129, v0
	v_mov_b32_e32 v130, v0
	v_mov_b32_e32 v131, v0
	s_movk_i32 s14, 15
.Lg3_sw2:
	s_waitcnt vmcnt(0)
	s_barrier
	s_xor_b32 s23, s23, 0x4000
	s_cmp_eq_u32 s14, 0
	s_cbranch_scc1 .Lg3_sw2_nb
	s_add_u32 m0, s5, s23
	s_nop 0
	global_load_lds_dwordx4 v180, s[8:9]
	s_add_u32 m0, m0, 0x1000
	s_add_u32 s20, s8, 0x10000
	s_addc_u32 s21, s9, 0
	global_load_lds_dwordx4 v180, s[20:21]
	s_add_u32 m0, m0, 0x1000
	s_add_u32 s20, s8, 0x20000
	s_addc_u32 s21, s9, 0
	global_load_lds_dwordx4 v180, s[20:21]
	s_add_u32 m0, m0, 0x1000
	s_add_u32 s20, s8, 0x30000
	s_addc_u32 s21, s9, 0
	global_load_lds_dwordx4 v180, s[20:21]
	s_add_u32 s8, s8, 0x80
	s_addc_u32 s9, s9, 0
.Lg3_sw2_nb:
	ds_read_b128 v[132:135], v181 offset:0
	ds_read_b128 v[136:139], v181 offset:2048
	ds_read_b128 v[140:143], v181 offset:4096
	ds_read_b128 v[144:147], v181 offset:6144
	ds_read_b128 v[148:151], v181 offset:8192
	ds_read_b128 v[152:155], v181 offset:10240
	ds_read_b128 v[156:159], v181 offset:12288
	ds_read_b128 v[160:163], v181 offset:14336
	ds_read_b128 v[164:167], v208 offset:0
	ds_read_b128 v[168:171], v208 offset:2048
	ds_read_b128 v[172:175], v208 offset:4096
	ds_read_b128 v[176:179], v208 offset:6144
	ds_read_b128 v[224:227], v208 offset:8192
	ds_read_b128 v[228:231], v208 offset:10240
	s_waitcnt lgkmcnt(6)
	ds_read_b128 v[234:237], v208 offset:12288
	ds_read_b128 v[238:241], v208 offset:14336
	ds_read_b128 v[242:245], v223 offset:32768
	ds_read_b128 v[112:115], v223 offset:34816
	s_waitcnt lgkmcnt(2)
	s_barrier
	s_cmp_eq_u32 s14, 0
	s_cbranch_scc1 .Lg3_sw2_nl
	s_add_u32 m0, s5, 0x0
	s_nop 0
	global_load_lds_dwordx4 v180, s[2:3]
	s_add_u32 m0, s5, 0x1000
	s_add_u32 s20, s2, 0x10000
	s_addc_u32 s21, s3, 0
	global_load_lds_dwordx4 v180, s[20:21]
	s_add_u32 m0, s5, 0x2000
	s_add_u32 s20, s2, 0x20000
	s_addc_u32 s21, s3, 0
	global_load_lds_dwordx4 v180, s[20:21]
	s_add_u32 m0, s5, 0x3000
	s_add_u32 s20, s2, 0x30000
	s_addc_u32 s21, s3, 0
	global_load_lds_dwordx4 v180, s[20:21]
	s_add_u32 m0, s5, 0x4000
	s_add_u32 s20, s2, 0x40000
	s_addc_u32 s21, s3, 0
	global_load_lds_dwordx4 v180, s[20:21]
	s_add_u32 m0, s5, 0x5000
	s_add_u32 s20, s2, 0x50000
	s_addc_u32 s21, s3, 0
	global_load_lds_dwordx4 v180, s[20:21]
	s_add_u32 m0, s5, 0x6000
	s_add_u32 s20, s2, 0x60000
	s_addc_u32 s21, s3, 0
	global_load_lds_dwordx4 v180, s[20:21]
	s_add_u32 m0, s5, 0x7000
	s_add_u32 s20, s2, 0x70000
	s_addc_u32 s21, s3, 0
	global_load_lds_dwordx4 v180, s[20:21]
	s_add_u32 s2, s2, 0x80
	s_addc_u32 s3, s3, 0
.Lg3_sw2_nl:
	s_waitcnt lgkmcnt(1)
	v_mfma_f32_16x16x32_f16 v[0:3], v[132:135], v[242:245], v[0:3]
	v_mfma_f32_16x16x32_f16 v[16:19], v[136:139], v[242:245], v[16:19]
	v_mfma_f32_16x16x32_f16 v[32:35], v[140:143], v[242:245], v[32:35]
	v_mfma_f32_16x16x32_f16 v[48:51], v[144:147], v[242:245], v[48:51]
	v_mfma_f32_16x16x32_f16 v[64:67], v[148:151], v[242:245], v[64:67]
	v_mfma_f32_16x16x32_f16 v[80:83], v[152:155], v[242:245], v[80:83]
	v_mfma_f32_16x16x32_f16 v[96:99], v[156:159], v[242:245], v[96:99]
	v_mfma_f32_16x16x32_f16 v[116:119], v[160:163], v[242:245], v[116:119]
	ds_read_b128 v[242:245], v223 offset:36864
	s_waitcnt lgkmcnt(1)
	v_mfma_f32_16x16x32_f16 v[4:7], v[132:135], v[112:115], v[4:7]
	v_mfma_f32_16x16x32_f16 v[20:23], v[136:139], v[112:115], v[20:23]
	v_mfma_f32_16x16x32_f16 v[36:39], v[140:143], v[112:115], v[36:39]
	v_mfma_f32_16x16x32_f16 v[52:55], v[144:147], v[112:115], v[52:55]
	v_mfma_f32_16x16x32_f16 v[68:71], v[148:151], v[112:115], v[68:71]
	v_mfma_f32_16x16x32_f16 v[84:87], v[152:155], v[112:115], v[84:87]
	v_mfma_f32_16x16x32_f16 v[100:103], v[156:159], v[112:115], v[100:103]
	v_mfma_f32_16x16x32_f16 v[120:123], v[160:163], v[112:115], v[120:123]
	ds_read_b128 v[112:115], v223 offset:38912
	s_waitcnt lgkmcnt(1)
	v_mfma_f32_16x16x32_f16 v[8:11], v[132:135], v[242:245], v[8:11]
	v_mfma_f32_16x16x32_f16 v[24:27], v[136:139], v[242:245], v[24:27]
	v_mfma_f32_16x16x32_f16 v[40:43], v[140:143], v[242:245], v[40:43]
	v_mfma_f32_16x16x32_f16 v[56:59], v[144:147], v[242:245], v[56:59]
	v_mfma_f32_16x16x32_f16 v[72:75], v[148:151], v[242:245], v[72:75]
	v_mfma_f32_16x16x32_f16 v[88:91], v[152:155], v[242:245], v[88:91]
	v_mfma_f32_16x16x32_f16 v[104:107], v[156:159], v[242:245], v[104:107]
	v_mfma_f32_16x16x32_f16 v[124:127], v[160:163], v[242:245], v[124:127]
	ds_read_b128 v[242:245], v233 offset:32768
	s_waitcnt lgkmcnt(1)
	v_mfma_f32_16x16x32_f16 v[12:15], v[132:135], v[112:115], v[12:15]
	v_mfma_f32_16x16x32_f16 v[28:31], v[136:139], v[112:115], v[28:31]
	v_mfma_f32_16x16x32_f16 v[44:47], v[140:143], v[112:115], v[44:47]
	v_mfma_f32_16x16x32_f16 v[60:63], v[144:147], v[112:115], v[60:63]
	v_mfma_f32_16x16x32_f16 v[76:79], v[148:151], v[112:115], v[76:79]
	v_mfma_f32_16x16x32_f16 v[92:95], v[152:155], v[112:115], v[92:95]
	v_mfma_f32_16x16x32_f16 v[108:111], v[156:159], v[112:115], v[108:111]
	v_mfma_f32_16x16x32_f16 v[128:131], v[160:163], v[112:115], v[128:131]
	ds_read_b128 v[112:115], v233 offset:34816
	s_waitcnt lgkmcnt(1)
	v_mfma_f32_16x16x32_f16 v[0:3], v[164:167], v[242:245], v[0:3]
	v_mfma_f32_16x16x32_f16 v[16:19], v[168:171], v[242:245], v[16:19]
	v_mfma_f32_16x16x32_f16 v[32:35], v[172:175], v[242:245], v[32:35]
	v_mfma_f32_16x16x32_f16 v[48:51], v[176:179], v[242:245], v[48:51]
	v_mfma_f32_16x16x32_f16 v[64:67], v[224:227], v[242:245], v[64:67]
	v_mfma_f32_16x16x32_f16 v[80:83], v[228:231], v[242:245], v[80:83]
	v_mfma_f32_16x16x32_f16 v[96:99], v[234:237], v[242:245], v[96:99]
	v_mfma_f32_16x16x32_f16 v[116:119], v[238:241], v[242:245], v[116:119]
	ds_read_b128 v[242:245], v233 offset:36864
	s_waitcnt lgkmcnt(1)
	v_mfma_f32_16x16x32_f16 v[4:7], v[164:167], v[112:115], v[4:7]
	v_mfma_f32_16x16x32_f16 v[20:23], v[168:171], v[112:115], v[20:23]
	v_mfma_f32_16x16x32_f16 v[36:39], v[172:175], v[112:115], v[36:39]
	v_mfma_f32_16x16x32_f16 v[52:55], v[176:179], v[112:115], v[52:55]
	v_mfma_f32_16x16x32_f16 v[68:71], v[224:227], v[112:115], v[68:71]
	v_mfma_f32_16x16x32_f16 v[84:87], v[228:231], v[112:115], v[84:87]
	v_mfma_f32_16x16x32_f16 v[100:103], v[234:237], v[112:115], v[100:103]
	v_mfma_f32_16x16x32_f16 v[120:123], v[238:241], v[112:115], v[120:123]
	ds_read_b128 v[112:115], v233 offset:38912
	s_waitcnt lgkmcnt(1)
	v_mfma_f32_16x16x32_f16 v[8:11], v[164:167], v[242:245], v[8:11]
	v_mfma_f32_16x16x32_f16 v[24:27], v[168:171], v[242:245], v[24:27]
	v_mfma_f32_16x16x32_f16 v[40:43], v[172:175], v[242:245], v[40:43]
	v_mfma_f32_16x16x32_f16 v[56:59], v[176:179], v[242:245], v[56:59]
	v_mfma_f32_16x16x32_f16 v[72:75], v[224:227], v[242:245], v[72:75]
	v_mfma_f32_16x16x32_f16 v[88:91], v[228:231], v[242:245], v[88:91]
	v_mfma_f32_16x16x32_f16 v[104:107], v[234:237], v[242:245], v[104:107]
	v_mfma_f32_16x16x32_f16 v[124:127], v[238:241], v[242:245], v[124:127]
	s_waitcnt lgkmcnt(0)
	v_mfma_f32_16x16x32_f16 v[12:15], v[164:167], v[112:115], v[12:15]
	v_mfma_f32_16x16x32_f16 v[28:31], v[168:171], v[112:115], v[28:31]
	v_mfma_f32_16x16x32_f16 v[44:47], v[172:175], v[112:115], v[44:47]
	v_mfma_f32_16x16x32_f16 v[60:63], v[176:179], v[112:115], v[60:63]
	v_mfma_f32_16x16x32_f16 v[76:79], v[224:227], v[112:115], v[76:79]
	v_mfma_f32_16x16x32_f16 v[92:95], v[228:231], v[112:115], v[92:95]
	v_mfma_f32_16x16x32_f16 v[108:111], v[234:237], v[112:115], v[108:111]
	v_mfma_f32_16x16x32_f16 v[128:131], v[238:241], v[112:115], v[128:131]
	v_xor_b32_e32 v223, 0x4000, v223
	v_xor_b32_e32 v233, 0x4000, v233
	s_sub_u32 s14, s14, 1
	s_cmp_lg_u32 s14, -1
	s_cbranch_scc1 .Lg3_sw2
	s_nop 7
	s_mov_b64 s[100:101], s[98:99]
	v_mul_f32_e32 v132, 0xbfb8aa3b, v0
	v_exp_f32_e32 v132, v132
	s_nop 0
	v_add_f32_e32 v133, 1.0, v132
	v_div_scale_f32 v134, s[2:3], v133, v133, v0
	v_rcp_f32_e32 v135, v134
	v_div_scale_f32 v136, vcc, v0, v133, v0
	v_fma_f32 v137, -v134, v135, 1.0
	v_fmac_f32_e32 v135, v137, v135
	v_mul_f32_e32 v138, v136, v135
	v_fma_f32 v137, -v134, v138, v136
	v_fmac_f32_e32 v138, v137, v135
	v_fma_f32 v134, -v134, v138, v136
	v_div_fmas_f32 v134, v134, v135, v138
	v_div_fixup_f32 v134, v134, v133, v0
	v_mul_f32_e32 v134, v8, v134
	v_med3_f32 v134, v134, s57, v194
	v_cvt_f16_f32_e32 v139, v134
	v_mul_f32_e32 v132, 0xbfb8aa3b, v4
	v_exp_f32_e32 v132, v132
	s_nop 0
	v_add_f32_e32 v133, 1.0, v132
	v_div_scale_f32 v134, s[2:3], v133, v133, v4
	v_rcp_f32_e32 v135, v134
	v_div_scale_f32 v136, vcc, v4, v133, v4
	v_fma_f32 v137, -v134, v135, 1.0
	v_fmac_f32_e32 v135, v137, v135
	v_mul_f32_e32 v138, v136, v135
	v_fma_f32 v137, -v134, v138, v136
	v_fmac_f32_e32 v138, v137, v135
	v_fma_f32 v134, -v134, v138, v136
	v_div_fmas_f32 v134, v134, v135, v138
	v_div_fixup_f32 v134, v134, v133, v4
	v_mul_f32_e32 v134, v12, v134
	v_med3_f32 v134, v134, s57, v194
	v_cvt_f16_f32_e32 v140, v134
	global_store_short v246, v139, s[100:101]
	global_store_short v246, v140, s[100:101] offset:32
	s_add_u32 s100, s98, 0x1600
	s_addc_u32 s101, s99, 0
	v_mul_f32_e32 v132, 0xbfb8aa3b, v1
	v_exp_f32_e32 v132, v132
	s_nop 0
	v_add_f32_e32 v133, 1.0, v132
	v_div_scale_f32 v134, s[2:3], v133, v133, v1
	v_rcp_f32_e32 v135, v134
	v_div_scale_f32 v136, vcc, v1, v133, v1
	v_fma_f32 v137, -v134, v135, 1.0
	v_fmac_f32_e32 v135, v137, v135
	v_mul_f32_e32 v138, v136, v135
	v_fma_f32 v137, -v134, v138, v136
	v_fmac_f32_e32 v138, v137, v135
	v_fma_f32 v134, -v134, v138, v136
	v_div_fmas_f32 v134, v134, v135, v138
	v_div_fixup_f32 v134, v134, v133, v1
	v_mul_f32_e32 v134, v9, v134
	v_med3_f32 v134, v134, s57, v194
	v_cvt_f16_f32_e32 v139, v134
	v_mul_f32_e32 v132, 0xbfb8aa3b, v5
	v_exp_f32_e32 v132, v132
	s_nop 0
	v_add_f32_e32 v133, 1.0, v132
	v_div_scale_f32 v134, s[2:3], v133, v133, v5
	v_rcp_f32_e32 v135, v134
	v_div_scale_f32 v136, vcc, v5, v133, v5
	v_fma_f32 v137, -v134, v135, 1.0
	v_fmac_f32_e32 v135, v137, v135
	v_mul_f32_e32 v138, v136, v135
	v_fma_f32 v137, -v134, v138, v136
	v_fmac_f32_e32 v138, v137, v135
	v_fma_f32 v134, -v134, v138, v136
	v_div_fmas_f32 v134, v134, v135, v138
	v_div_fixup_f32 v134, v134, v133, v5
	v_mul_f32_e32 v134, v13, v134
	v_med3_f32 v134, v134, s57, v194
	v_cvt_f16_f32_e32 v140, v134
	global_store_short v246, v139, s[100:101]
	global_store_short v246, v140, s[100:101] offset:32
	s_add_u32 s100, s98, 0x2c00
	s_addc_u32 s101, s99, 0
	v_mul_f32_e32 v132, 0xbfb8aa3b, v2
	v_exp_f32_e32 v132, v132
	s_nop 0
	v_add_f32_e32 v133, 1.0, v132
	v_div_scale_f32 v134, s[2:3], v133, v133, v2
	v_rcp_f32_e32 v135, v134
	v_div_scale_f32 v136, vcc, v2, v133, v2
	v_fma_f32 v137, -v134, v135, 1.0
	v_fmac_f32_e32 v135, v137, v135
	v_mul_f32_e32 v138, v136, v135
	v_fma_f32 v137, -v134, v138, v136
	v_fmac_f32_e32 v138, v137, v135
	v_fma_f32 v134, -v134, v138, v136
	v_div_fmas_f32 v134, v134, v135, v138
	v_div_fixup_f32 v134, v134, v133, v2
	v_mul_f32_e32 v134, v10, v134
	v_med3_f32 v134, v134, s57, v194
	v_cvt_f16_f32_e32 v139, v134
	v_mul_f32_e32 v132, 0xbfb8aa3b, v6
	v_exp_f32_e32 v132, v132
	s_nop 0
	v_add_f32_e32 v133, 1.0, v132
	v_div_scale_f32 v134, s[2:3], v133, v133, v6
	v_rcp_f32_e32 v135, v134
	v_div_scale_f32 v136, vcc, v6, v133, v6
	v_fma_f32 v137, -v134, v135, 1.0
	v_fmac_f32_e32 v135, v137, v135
	v_mul_f32_e32 v138, v136, v135
	v_fma_f32 v137, -v134, v138, v136
	v_fmac_f32_e32 v138, v137, v135
	v_fma_f32 v134, -v134, v138, v136
	v_div_fmas_f32 v134, v134, v135, v138
	v_div_fixup_f32 v134, v134, v133, v6
	v_mul_f32_e32 v134, v14, v134
	v_med3_f32 v134, v134, s57, v194
	v_cvt_f16_f32_e32 v140, v134
	global_store_short v246, v139, s[100:101]
	global_store_short v246, v140, s[100:101] offset:32
	s_add_u32 s100, s98, 0x4200
	s_addc_u32 s101, s99, 0
	v_mul_f32_e32 v132, 0xbfb8aa3b, v3
	v_exp_f32_e32 v132, v132
	s_nop 0
	v_add_f32_e32 v133, 1.0, v132
	v_div_scale_f32 v134, s[2:3], v133, v133, v3
	v_rcp_f32_e32 v135, v134
	v_div_scale_f32 v136, vcc, v3, v133, v3
	v_fma_f32 v137, -v134, v135, 1.0
	v_fmac_f32_e32 v135, v137, v135
	v_mul_f32_e32 v138, v136, v135
	v_fma_f32 v137, -v134, v138, v136
	v_fmac_f32_e32 v138, v137, v135
	v_fma_f32 v134, -v134, v138, v136
	v_div_fmas_f32 v134, v134, v135, v138
	v_div_fixup_f32 v134, v134, v133, v3
	v_mul_f32_e32 v134, v11, v134
	v_med3_f32 v134, v134, s57, v194
	v_cvt_f16_f32_e32 v139, v134
	v_mul_f32_e32 v132, 0xbfb8aa3b, v7
	v_exp_f32_e32 v132, v132
	s_nop 0
	v_add_f32_e32 v133, 1.0, v132
	v_div_scale_f32 v134, s[2:3], v133, v133, v7
	v_rcp_f32_e32 v135, v134
	v_div_scale_f32 v136, vcc, v7, v133, v7
	v_fma_f32 v137, -v134, v135, 1.0
	v_fmac_f32_e32 v135, v137, v135
	v_mul_f32_e32 v138, v136, v135
	v_fma_f32 v137, -v134, v138, v136
	v_fmac_f32_e32 v138, v137, v135
	v_fma_f32 v134, -v134, v138, v136
	v_div_fmas_f32 v134, v134, v135, v138
	v_div_fixup_f32 v134, v134, v133, v7
	v_mul_f32_e32 v134, v15, v134
	v_med3_f32 v134, v134, s57, v194
	v_cvt_f16_f32_e32 v140, v134
	global_store_short v246, v139, s[100:101]
	global_store_short v246, v140, s[100:101] offset:32
	s_add_u32 s100, s98, 0x16000
	s_addc_u32 s101, s99, 0
	v_mul_f32_e32 v132, 0xbfb8aa3b, v16
	v_exp_f32_e32 v132, v132
	s_nop 0
	v_add_f32_e32 v133, 1.0, v132
	v_div_scale_f32 v134, s[2:3], v133, v133, v16
	v_rcp_f32_e32 v135, v134
	v_div_scale_f32 v136, vcc, v16, v133, v16
	v_fma_f32 v137, -v134, v135, 1.0
	v_fmac_f32_e32 v135, v137, v135
	v_mul_f32_e32 v138, v136, v135
	v_fma_f32 v137, -v134, v138, v136
	v_fmac_f32_e32 v138, v137, v135
	v_fma_f32 v134, -v134, v138, v136
	v_div_fmas_f32 v134, v134, v135, v138
	v_div_fixup_f32 v134, v134, v133, v16
	v_mul_f32_e32 v134, v24, v134
	v_med3_f32 v134, v134, s57, v194
	v_cvt_f16_f32_e32 v139, v134
	v_mul_f32_e32 v132, 0xbfb8aa3b, v20
	v_exp_f32_e32 v132, v132
	s_nop 0
	v_add_f32_e32 v133, 1.0, v132
	v_div_scale_f32 v134, s[2:3], v133, v133, v20
	v_rcp_f32_e32 v135, v134
	v_div_scale_f32 v136, vcc, v20, v133, v20
	v_fma_f32 v137, -v134, v135, 1.0
	v_fmac_f32_e32 v135, v137, v135
	v_mul_f32_e32 v138, v136, v135
	v_fma_f32 v137, -v134, v138, v136
	v_fmac_f32_e32 v138, v137, v135
	v_fma_f32 v134, -v134, v138, v136
	v_div_fmas_f32 v134, v134, v135, v138
	v_div_fixup_f32 v134, v134, v133, v20
	v_mul_f32_e32 v134, v28, v134
	v_med3_f32 v134, v134, s57, v194
	v_cvt_f16_f32_e32 v140, v134
	global_store_short v246, v139, s[100:101]
	global_store_short v246, v140, s[100:101] offset:32
	s_add_u32 s100, s98, 0x17600
	s_addc_u32 s101, s99, 0
	v_mul_f32_e32 v132, 0xbfb8aa3b, v17
	v_exp_f32_e32 v132, v132
	s_nop 0
	v_add_f32_e32 v133, 1.0, v132
	v_div_scale_f32 v134, s[2:3], v133, v133, v17
	v_rcp_f32_e32 v135, v134
	v_div_scale_f32 v136, vcc, v17, v133, v17
	v_fma_f32 v137, -v134, v135, 1.0
	v_fmac_f32_e32 v135, v137, v135
	v_mul_f32_e32 v138, v136, v135
	v_fma_f32 v137, -v134, v138, v136
	v_fmac_f32_e32 v138, v137, v135
	v_fma_f32 v134, -v134, v138, v136
	v_div_fmas_f32 v134, v134, v135, v138
	v_div_fixup_f32 v134, v134, v133, v17
	v_mul_f32_e32 v134, v25, v134
	v_med3_f32 v134, v134, s57, v194
	v_cvt_f16_f32_e32 v139, v134
	v_mul_f32_e32 v132, 0xbfb8aa3b, v21
	v_exp_f32_e32 v132, v132
	s_nop 0
	v_add_f32_e32 v133, 1.0, v132
	v_div_scale_f32 v134, s[2:3], v133, v133, v21
	v_rcp_f32_e32 v135, v134
	v_div_scale_f32 v136, vcc, v21, v133, v21
	v_fma_f32 v137, -v134, v135, 1.0
	v_fmac_f32_e32 v135, v137, v135
	v_mul_f32_e32 v138, v136, v135
	v_fma_f32 v137, -v134, v138, v136
	v_fmac_f32_e32 v138, v137, v135
	v_fma_f32 v134, -v134, v138, v136
	v_div_fmas_f32 v134, v134, v135, v138
	v_div_fixup_f32 v134, v134, v133, v21
	v_mul_f32_e32 v134, v29, v134
	v_med3_f32 v134, v134, s57, v194
	v_cvt_f16_f32_e32 v140, v134
	global_store_short v246, v139, s[100:101]
	global_store_short v246, v140, s[100:101] offset:32
	s_add_u32 s100, s98, 0x18c00
	s_addc_u32 s101, s99, 0
	v_mul_f32_e32 v132, 0xbfb8aa3b, v18
	v_exp_f32_e32 v132, v132
	s_nop 0
	v_add_f32_e32 v133, 1.0, v132
	v_div_scale_f32 v134, s[2:3], v133, v133, v18
	v_rcp_f32_e32 v135, v134
	v_div_scale_f32 v136, vcc, v18, v133, v18
	v_fma_f32 v137, -v134, v135, 1.0
	v_fmac_f32_e32 v135, v137, v135
	v_mul_f32_e32 v138, v136, v135
	v_fma_f32 v137, -v134, v138, v136
	v_fmac_f32_e32 v138, v137, v135
	v_fma_f32 v134, -v134, v138, v136
	v_div_fmas_f32 v134, v134, v135, v138
	v_div_fixup_f32 v134, v134, v133, v18
	v_mul_f32_e32 v134, v26, v134
	v_med3_f32 v134, v134, s57, v194
	v_cvt_f16_f32_e32 v139, v134
	v_mul_f32_e32 v132, 0xbfb8aa3b, v22
	v_exp_f32_e32 v132, v132
	s_nop 0
	v_add_f32_e32 v133, 1.0, v132
	v_div_scale_f32 v134, s[2:3], v133, v133, v22
	v_rcp_f32_e32 v135, v134
	v_div_scale_f32 v136, vcc, v22, v133, v22
	v_fma_f32 v137, -v134, v135, 1.0
	v_fmac_f32_e32 v135, v137, v135
	v_mul_f32_e32 v138, v136, v135
	v_fma_f32 v137, -v134, v138, v136
	v_fmac_f32_e32 v138, v137, v135
	v_fma_f32 v134, -v134, v138, v136
	v_div_fmas_f32 v134, v134, v135, v138
	v_div_fixup_f32 v134, v134, v133, v22
	v_mul_f32_e32 v134, v30, v134
	v_med3_f32 v134, v134, s57, v194
	v_cvt_f16_f32_e32 v140, v134
	global_store_short v246, v139, s[100:101]
	global_store_short v246, v140, s[100:101] offset:32
	s_add_u32 s100, s98, 0x1a200
	s_addc_u32 s101, s99, 0
	v_mul_f32_e32 v132, 0xbfb8aa3b, v19
	v_exp_f32_e32 v132, v132
	s_nop 0
	v_add_f32_e32 v133, 1.0, v132
	v_div_scale_f32 v134, s[2:3], v133, v133, v19
	v_rcp_f32_e32 v135, v134
	v_div_scale_f32 v136, vcc, v19, v133, v19
	v_fma_f32 v137, -v134, v135, 1.0
	v_fmac_f32_e32 v135, v137, v135
	v_mul_f32_e32 v138, v136, v135
	v_fma_f32 v137, -v134, v138, v136
	v_fmac_f32_e32 v138, v137, v135
	v_fma_f32 v134, -v134, v138, v136
	v_div_fmas_f32 v134, v134, v135, v138
	v_div_fixup_f32 v134, v134, v133, v19
	v_mul_f32_e32 v134, v27, v134
	v_med3_f32 v134, v134, s57, v194
	v_cvt_f16_f32_e32 v139, v134
	v_mul_f32_e32 v132, 0xbfb8aa3b, v23
	v_exp_f32_e32 v132, v132
	s_nop 0
	v_add_f32_e32 v133, 1.0, v132
	v_div_scale_f32 v134, s[2:3], v133, v133, v23
	v_rcp_f32_e32 v135, v134
	v_div_scale_f32 v136, vcc, v23, v133, v23
	v_fma_f32 v137, -v134, v135, 1.0
	v_fmac_f32_e32 v135, v137, v135
	v_mul_f32_e32 v138, v136, v135
	v_fma_f32 v137, -v134, v138, v136
	v_fmac_f32_e32 v138, v137, v135
	v_fma_f32 v134, -v134, v138, v136
	v_div_fmas_f32 v134, v134, v135, v138
	v_div_fixup_f32 v134, v134, v133, v23
	v_mul_f32_e32 v134, v31, v134
	v_med3_f32 v134, v134, s57, v194
	v_cvt_f16_f32_e32 v140, v134
	global_store_short v246, v139, s[100:101]
	global_store_short v246, v140, s[100:101] offset:32
	s_add_u32 s100, s98, 0x2c000
	s_addc_u32 s101, s99, 0
	v_mul_f32_e32 v132, 0xbfb8aa3b, v32
	v_exp_f32_e32 v132, v132
	s_nop 0
	v_add_f32_e32 v133, 1.0, v132
	v_div_scale_f32 v134, s[2:3], v133, v133, v32
	v_rcp_f32_e32 v135, v134
	v_div_scale_f32 v136, vcc, v32, v133, v32
	v_fma_f32 v137, -v134, v135, 1.0
	v_fmac_f32_e32 v135, v137, v135
	v_mul_f32_e32 v138, v136, v135
	v_fma_f32 v137, -v134, v138, v136
	v_fmac_f32_e32 v138, v137, v135
	v_fma_f32 v134, -v134, v138, v136
	v_div_fmas_f32 v134, v134, v135, v138
	v_div_fixup_f32 v134, v134, v133, v32
	v_mul_f32_e32 v134, v40, v134
	v_med3_f32 v134, v134, s57, v194
	v_cvt_f16_f32_e32 v139, v134
	v_mul_f32_e32 v132, 0xbfb8aa3b, v36
	v_exp_f32_e32 v132, v132
	s_nop 0
	v_add_f32_e32 v133, 1.0, v132
	v_div_scale_f32 v134, s[2:3], v133, v133, v36
	v_rcp_f32_e32 v135, v134
	v_div_scale_f32 v136, vcc, v36, v133, v36
	v_fma_f32 v137, -v134, v135, 1.0
	v_fmac_f32_e32 v135, v137, v135
	v_mul_f32_e32 v138, v136, v135
	v_fma_f32 v137, -v134, v138, v136
	v_fmac_f32_e32 v138, v137, v135
	v_fma_f32 v134, -v134, v138, v136
	v_div_fmas_f32 v134, v134, v135, v138
	v_div_fixup_f32 v134, v134, v133, v36
	v_mul_f32_e32 v134, v44, v134
	v_med3_f32 v134, v134, s57, v194
	v_cvt_f16_f32_e32 v140, v134
	global_store_short v246, v139, s[100:101]
	global_store_short v246, v140, s[100:101] offset:32
	s_add_u32 s100, s98, 0x2d600
	s_addc_u32 s101, s99, 0
	v_mul_f32_e32 v132, 0xbfb8aa3b, v33
	v_exp_f32_e32 v132, v132
	s_nop 0
	v_add_f32_e32 v133, 1.0, v132
	v_div_scale_f32 v134, s[2:3], v133, v133, v33
	v_rcp_f32_e32 v135, v134
	v_div_scale_f32 v136, vcc, v33, v133, v33
	v_fma_f32 v137, -v134, v135, 1.0
	v_fmac_f32_e32 v135, v137, v135
	v_mul_f32_e32 v138, v136, v135
	v_fma_f32 v137, -v134, v138, v136
	v_fmac_f32_e32 v138, v137, v135
	v_fma_f32 v134, -v134, v138, v136
	v_div_fmas_f32 v134, v134, v135, v138
	v_div_fixup_f32 v134, v134, v133, v33
	v_mul_f32_e32 v134, v41, v134
	v_med3_f32 v134, v134, s57, v194
	v_cvt_f16_f32_e32 v139, v134
	v_mul_f32_e32 v132, 0xbfb8aa3b, v37
	v_exp_f32_e32 v132, v132
	s_nop 0
	v_add_f32_e32 v133, 1.0, v132
	v_div_scale_f32 v134, s[2:3], v133, v133, v37
	v_rcp_f32_e32 v135, v134
	v_div_scale_f32 v136, vcc, v37, v133, v37
	v_fma_f32 v137, -v134, v135, 1.0
	v_fmac_f32_e32 v135, v137, v135
	v_mul_f32_e32 v138, v136, v135
	v_fma_f32 v137, -v134, v138, v136
	v_fmac_f32_e32 v138, v137, v135
	v_fma_f32 v134, -v134, v138, v136
	v_div_fmas_f32 v134, v134, v135, v138
	v_div_fixup_f32 v134, v134, v133, v37
	v_mul_f32_e32 v134, v45, v134
	v_med3_f32 v134, v134, s57, v194
	v_cvt_f16_f32_e32 v140, v134
	global_store_short v246, v139, s[100:101]
	global_store_short v246, v140, s[100:101] offset:32
	s_add_u32 s100, s98, 0x2ec00
	s_addc_u32 s101, s99, 0
	v_mul_f32_e32 v132, 0xbfb8aa3b, v34
	v_exp_f32_e32 v132, v132
	s_nop 0
	v_add_f32_e32 v133, 1.0, v132
	v_div_scale_f32 v134, s[2:3], v133, v133, v34
	v_rcp_f32_e32 v135, v134
	v_div_scale_f32 v136, vcc, v34, v133, v34
	v_fma_f32 v137, -v134, v135, 1.0
	v_fmac_f32_e32 v135, v137, v135
	v_mul_f32_e32 v138, v136, v135
	v_fma_f32 v137, -v134, v138, v136
	v_fmac_f32_e32 v138, v137, v135
	v_fma_f32 v134, -v134, v138, v136
	v_div_fmas_f32 v134, v134, v135, v138
	v_div_fixup_f32 v134, v134, v133, v34
	v_mul_f32_e32 v134, v42, v134
	v_med3_f32 v134, v134, s57, v194
	v_cvt_f16_f32_e32 v139, v134
	v_mul_f32_e32 v132, 0xbfb8aa3b, v38
	v_exp_f32_e32 v132, v132
	s_nop 0
	v_add_f32_e32 v133, 1.0, v132
	v_div_scale_f32 v134, s[2:3], v133, v133, v38
	v_rcp_f32_e32 v135, v134
	v_div_scale_f32 v136, vcc, v38, v133, v38
	v_fma_f32 v137, -v134, v135, 1.0
	v_fmac_f32_e32 v135, v137, v135
	v_mul_f32_e32 v138, v136, v135
	v_fma_f32 v137, -v134, v138, v136
	v_fmac_f32_e32 v138, v137, v135
	v_fma_f32 v134, -v134, v138, v136
	v_div_fmas_f32 v134, v134, v135, v138
	v_div_fixup_f32 v134, v134, v133, v38
	v_mul_f32_e32 v134, v46, v134
	v_med3_f32 v134, v134, s57, v194
	v_cvt_f16_f32_e32 v140, v134
	global_store_short v246, v139, s[100:101]
	global_store_short v246, v140, s[100:101] offset:32
	s_add_u32 s100, s98, 0x30200
	s_addc_u32 s101, s99, 0
	v_mul_f32_e32 v132, 0xbfb8aa3b, v35
	v_exp_f32_e32 v132, v132
	s_nop 0
	v_add_f32_e32 v133, 1.0, v132
	v_div_scale_f32 v134, s[2:3], v133, v133, v35
	v_rcp_f32_e32 v135, v134
	v_div_scale_f32 v136, vcc, v35, v133, v35
	v_fma_f32 v137, -v134, v135, 1.0
	v_fmac_f32_e32 v135, v137, v135
	v_mul_f32_e32 v138, v136, v135
	v_fma_f32 v137, -v134, v138, v136
	v_fmac_f32_e32 v138, v137, v135
	v_fma_f32 v134, -v134, v138, v136
	v_div_fmas_f32 v134, v134, v135, v138
	v_div_fixup_f32 v134, v134, v133, v35
	v_mul_f32_e32 v134, v43, v134
	v_med3_f32 v134, v134, s57, v194
	v_cvt_f16_f32_e32 v139, v134
	v_mul_f32_e32 v132, 0xbfb8aa3b, v39
	v_exp_f32_e32 v132, v132
	s_nop 0
	v_add_f32_e32 v133, 1.0, v132
	v_div_scale_f32 v134, s[2:3], v133, v133, v39
	v_rcp_f32_e32 v135, v134
	v_div_scale_f32 v136, vcc, v39, v133, v39
	v_fma_f32 v137, -v134, v135, 1.0
	v_fmac_f32_e32 v135, v137, v135
	v_mul_f32_e32 v138, v136, v135
	v_fma_f32 v137, -v134, v138, v136
	v_fmac_f32_e32 v138, v137, v135
	v_fma_f32 v134, -v134, v138, v136
	v_div_fmas_f32 v134, v134, v135, v138
	v_div_fixup_f32 v134, v134, v133, v39
	v_mul_f32_e32 v134, v47, v134
	v_med3_f32 v134, v134, s57, v194
	v_cvt_f16_f32_e32 v140, v134
	global_store_short v246, v139, s[100:101]
	global_store_short v246, v140, s[100:101] offset:32
	s_add_u32 s100, s98, 0x42000
	s_addc_u32 s101, s99, 0
	v_mul_f32_e32 v132, 0xbfb8aa3b, v48
	v_exp_f32_e32 v132, v132
	s_nop 0
	v_add_f32_e32 v133, 1.0, v132
	v_div_scale_f32 v134, s[2:3], v133, v133, v48
	v_rcp_f32_e32 v135, v134
	v_div_scale_f32 v136, vcc, v48, v133, v48
	v_fma_f32 v137, -v134, v135, 1.0
	v_fmac_f32_e32 v135, v137, v135
	v_mul_f32_e32 v138, v136, v135
	v_fma_f32 v137, -v134, v138, v136
	v_fmac_f32_e32 v138, v137, v135
	v_fma_f32 v134, -v134, v138, v136
	v_div_fmas_f32 v134, v134, v135, v138
	v_div_fixup_f32 v134, v134, v133, v48
	v_mul_f32_e32 v134, v56, v134
	v_med3_f32 v134, v134, s57, v194
	v_cvt_f16_f32_e32 v139, v134
	v_mul_f32_e32 v132, 0xbfb8aa3b, v52
	v_exp_f32_e32 v132, v132
	s_nop 0
	v_add_f32_e32 v133, 1.0, v132
	v_div_scale_f32 v134, s[2:3], v133, v133, v52
	v_rcp_f32_e32 v135, v134
	v_div_scale_f32 v136, vcc, v52, v133, v52
	v_fma_f32 v137, -v134, v135, 1.0
	v_fmac_f32_e32 v135, v137, v135
	v_mul_f32_e32 v138, v136, v135
	v_fma_f32 v137, -v134, v138, v136
	v_fmac_f32_e32 v138, v137, v135
	v_fma_f32 v134, -v134, v138, v136
	v_div_fmas_f32 v134, v134, v135, v138
	v_div_fixup_f32 v134, v134, v133, v52
	v_mul_f32_e32 v134, v60, v134
	v_med3_f32 v134, v134, s57, v194
	v_cvt_f16_f32_e32 v140, v134
	global_store_short v246, v139, s[100:101]
	global_store_short v246, v140, s[100:101] offset:32
	s_add_u32 s100, s98, 0x43600
	s_addc_u32 s101, s99, 0
	v_mul_f32_e32 v132, 0xbfb8aa3b, v49
	v_exp_f32_e32 v132, v132
	s_nop 0
	v_add_f32_e32 v133, 1.0, v132
	v_div_scale_f32 v134, s[2:3], v133, v133, v49
	v_rcp_f32_e32 v135, v134
	v_div_scale_f32 v136, vcc, v49, v133, v49
	v_fma_f32 v137, -v134, v135, 1.0
	v_fmac_f32_e32 v135, v137, v135
	v_mul_f32_e32 v138, v136, v135
	v_fma_f32 v137, -v134, v138, v136
	v_fmac_f32_e32 v138, v137, v135
	v_fma_f32 v134, -v134, v138, v136
	v_div_fmas_f32 v134, v134, v135, v138
	v_div_fixup_f32 v134, v134, v133, v49
	v_mul_f32_e32 v134, v57, v134
	v_med3_f32 v134, v134, s57, v194
	v_cvt_f16_f32_e32 v139, v134
	v_mul_f32_e32 v132, 0xbfb8aa3b, v53
	v_exp_f32_e32 v132, v132
	s_nop 0
	v_add_f32_e32 v133, 1.0, v132
	v_div_scale_f32 v134, s[2:3], v133, v133, v53
	v_rcp_f32_e32 v135, v134
	v_div_scale_f32 v136, vcc, v53, v133, v53
	v_fma_f32 v137, -v134, v135, 1.0
	v_fmac_f32_e32 v135, v137, v135
	v_mul_f32_e32 v138, v136, v135
	v_fma_f32 v137, -v134, v138, v136
	v_fmac_f32_e32 v138, v137, v135
	v_fma_f32 v134, -v134, v138, v136
	v_div_fmas_f32 v134, v134, v135, v138
	v_div_fixup_f32 v134, v134, v133, v53
	v_mul_f32_e32 v134, v61, v134
	v_med3_f32 v134, v134, s57, v194
	v_cvt_f16_f32_e32 v140, v134
	global_store_short v246, v139, s[100:101]
	global_store_short v246, v140, s[100:101] offset:32
	s_add_u32 s100, s98, 0x44c00
	s_addc_u32 s101, s99, 0
	v_mul_f32_e32 v132, 0xbfb8aa3b, v50
	v_exp_f32_e32 v132, v132
	s_nop 0
	v_add_f32_e32 v133, 1.0, v132
	v_div_scale_f32 v134, s[2:3], v133, v133, v50
	v_rcp_f32_e32 v135, v134
	v_div_scale_f32 v136, vcc, v50, v133, v50
	v_fma_f32 v137, -v134, v135, 1.0
	v_fmac_f32_e32 v135, v137, v135
	v_mul_f32_e32 v138, v136, v135
	v_fma_f32 v137, -v134, v138, v136
	v_fmac_f32_e32 v138, v137, v135
	v_fma_f32 v134, -v134, v138, v136
	v_div_fmas_f32 v134, v134, v135, v138
	v_div_fixup_f32 v134, v134, v133, v50
	v_mul_f32_e32 v134, v58, v134
	v_med3_f32 v134, v134, s57, v194
	v_cvt_f16_f32_e32 v139, v134
	v_mul_f32_e32 v132, 0xbfb8aa3b, v54
	v_exp_f32_e32 v132, v132
	s_nop 0
	v_add_f32_e32 v133, 1.0, v132
	v_div_scale_f32 v134, s[2:3], v133, v133, v54
	v_rcp_f32_e32 v135, v134
	v_div_scale_f32 v136, vcc, v54, v133, v54
	v_fma_f32 v137, -v134, v135, 1.0
	v_fmac_f32_e32 v135, v137, v135
	v_mul_f32_e32 v138, v136, v135
	v_fma_f32 v137, -v134, v138, v136
	v_fmac_f32_e32 v138, v137, v135
	v_fma_f32 v134, -v134, v138, v136
	v_div_fmas_f32 v134, v134, v135, v138
	v_div_fixup_f32 v134, v134, v133, v54
	v_mul_f32_e32 v134, v62, v134
	v_med3_f32 v134, v134, s57, v194
	v_cvt_f16_f32_e32 v140, v134
	global_store_short v246, v139, s[100:101]
	global_store_short v246, v140, s[100:101] offset:32
	s_add_u32 s100, s98, 0x46200
	s_addc_u32 s101, s99, 0
	v_mul_f32_e32 v132, 0xbfb8aa3b, v51
	v_exp_f32_e32 v132, v132
	s_nop 0
	v_add_f32_e32 v133, 1.0, v132
	v_div_scale_f32 v134, s[2:3], v133, v133, v51
	v_rcp_f32_e32 v135, v134
	v_div_scale_f32 v136, vcc, v51, v133, v51
	v_fma_f32 v137, -v134, v135, 1.0
	v_fmac_f32_e32 v135, v137, v135
	v_mul_f32_e32 v138, v136, v135
	v_fma_f32 v137, -v134, v138, v136
	v_fmac_f32_e32 v138, v137, v135
	v_fma_f32 v134, -v134, v138, v136
	v_div_fmas_f32 v134, v134, v135, v138
	v_div_fixup_f32 v134, v134, v133, v51
	v_mul_f32_e32 v134, v59, v134
	v_med3_f32 v134, v134, s57, v194
	v_cvt_f16_f32_e32 v139, v134
	v_mul_f32_e32 v132, 0xbfb8aa3b, v55
	v_exp_f32_e32 v132, v132
	s_nop 0
	v_add_f32_e32 v133, 1.0, v132
	v_div_scale_f32 v134, s[2:3], v133, v133, v55
	v_rcp_f32_e32 v135, v134
	v_div_scale_f32 v136, vcc, v55, v133, v55
	v_fma_f32 v137, -v134, v135, 1.0
	v_fmac_f32_e32 v135, v137, v135
	v_mul_f32_e32 v138, v136, v135
	v_fma_f32 v137, -v134, v138, v136
	v_fmac_f32_e32 v138, v137, v135
	v_fma_f32 v134, -v134, v138, v136
	v_div_fmas_f32 v134, v134, v135, v138
	v_div_fixup_f32 v134, v134, v133, v55
	v_mul_f32_e32 v134, v63, v134
	v_med3_f32 v134, v134, s57, v194
	v_cvt_f16_f32_e32 v140, v134
	global_store_short v246, v139, s[100:101]
	global_store_short v246, v140, s[100:101] offset:32
	s_add_u32 s100, s98, 0x58000
	s_addc_u32 s101, s99, 0
	v_mul_f32_e32 v132, 0xbfb8aa3b, v64
	v_exp_f32_e32 v132, v132
	s_nop 0
	v_add_f32_e32 v133, 1.0, v132
	v_div_scale_f32 v134, s[2:3], v133, v133, v64
	v_rcp_f32_e32 v135, v134
	v_div_scale_f32 v136, vcc, v64, v133, v64
	v_fma_f32 v137, -v134, v135, 1.0
	v_fmac_f32_e32 v135, v137, v135
	v_mul_f32_e32 v138, v136, v135
	v_fma_f32 v137, -v134, v138, v136
	v_fmac_f32_e32 v138, v137, v135
	v_fma_f32 v134, -v134, v138, v136
	v_div_fmas_f32 v134, v134, v135, v138
	v_div_fixup_f32 v134, v134, v133, v64
	v_mul_f32_e32 v134, v72, v134
	v_med3_f32 v134, v134, s57, v194
	v_cvt_f16_f32_e32 v139, v134
	v_mul_f32_e32 v132, 0xbfb8aa3b, v68
	v_exp_f32_e32 v132, v132
	s_nop 0
	v_add_f32_e32 v133, 1.0, v132
	v_div_scale_f32 v134, s[2:3], v133, v133, v68
	v_rcp_f32_e32 v135, v134
	v_div_scale_f32 v136, vcc, v68, v133, v68
	v_fma_f32 v137, -v134, v135, 1.0
	v_fmac_f32_e32 v135, v137, v135
	v_mul_f32_e32 v138, v136, v135
	v_fma_f32 v137, -v134, v138, v136
	v_fmac_f32_e32 v138, v137, v135
	v_fma_f32 v134, -v134, v138, v136
	v_div_fmas_f32 v134, v134, v135, v138
	v_div_fixup_f32 v134, v134, v133, v68
	v_mul_f32_e32 v134, v76, v134
	v_med3_f32 v134, v134, s57, v194
	v_cvt_f16_f32_e32 v140, v134
	global_store_short v246, v139, s[100:101]
	global_store_short v246, v140, s[100:101] offset:32
	s_add_u32 s100, s98, 0x59600
	s_addc_u32 s101, s99, 0
	v_mul_f32_e32 v132, 0xbfb8aa3b, v65
	v_exp_f32_e32 v132, v132
	s_nop 0
	v_add_f32_e32 v133, 1.0, v132
	v_div_scale_f32 v134, s[2:3], v133, v133, v65
	v_rcp_f32_e32 v135, v134
	v_div_scale_f32 v136, vcc, v65, v133, v65
	v_fma_f32 v137, -v134, v135, 1.0
	v_fmac_f32_e32 v135, v137, v135
	v_mul_f32_e32 v138, v136, v135
	v_fma_f32 v137, -v134, v138, v136
	v_fmac_f32_e32 v138, v137, v135
	v_fma_f32 v134, -v134, v138, v136
	v_div_fmas_f32 v134, v134, v135, v138
	v_div_fixup_f32 v134, v134, v133, v65
	v_mul_f32_e32 v134, v73, v134
	v_med3_f32 v134, v134, s57, v194
	v_cvt_f16_f32_e32 v139, v134
	v_mul_f32_e32 v132, 0xbfb8aa3b, v69
	v_exp_f32_e32 v132, v132
	s_nop 0
	v_add_f32_e32 v133, 1.0, v132
	v_div_scale_f32 v134, s[2:3], v133, v133, v69
	v_rcp_f32_e32 v135, v134
	v_div_scale_f32 v136, vcc, v69, v133, v69
	v_fma_f32 v137, -v134, v135, 1.0
	v_fmac_f32_e32 v135, v137, v135
	v_mul_f32_e32 v138, v136, v135
	v_fma_f32 v137, -v134, v138, v136
	v_fmac_f32_e32 v138, v137, v135
	v_fma_f32 v134, -v134, v138, v136
	v_div_fmas_f32 v134, v134, v135, v138
	v_div_fixup_f32 v134, v134, v133, v69
	v_mul_f32_e32 v134, v77, v134
	v_med3_f32 v134, v134, s57, v194
	v_cvt_f16_f32_e32 v140, v134
	global_store_short v246, v139, s[100:101]
	global_store_short v246, v140, s[100:101] offset:32
	s_add_u32 s100, s98, 0x5ac00
	s_addc_u32 s101, s99, 0
	v_mul_f32_e32 v132, 0xbfb8aa3b, v66
	v_exp_f32_e32 v132, v132
	s_nop 0
	v_add_f32_e32 v133, 1.0, v132
	v_div_scale_f32 v134, s[2:3], v133, v133, v66
	v_rcp_f32_e32 v135, v134
	v_div_scale_f32 v136, vcc, v66, v133, v66
	v_fma_f32 v137, -v134, v135, 1.0
	v_fmac_f32_e32 v135, v137, v135
	v_mul_f32_e32 v138, v136, v135
	v_fma_f32 v137, -v134, v138, v136
	v_fmac_f32_e32 v138, v137, v135
	v_fma_f32 v134, -v134, v138, v136
	v_div_fmas_f32 v134, v134, v135, v138
	v_div_fixup_f32 v134, v134, v133, v66
	v_mul_f32_e32 v134, v74, v134
	v_med3_f32 v134, v134, s57, v194
	v_cvt_f16_f32_e32 v139, v134
	v_mul_f32_e32 v132, 0xbfb8aa3b, v70
	v_exp_f32_e32 v132, v132
	s_nop 0
	v_add_f32_e32 v133, 1.0, v132
	v_div_scale_f32 v134, s[2:3], v133, v133, v70
	v_rcp_f32_e32 v135, v134
	v_div_scale_f32 v136, vcc, v70, v133, v70
	v_fma_f32 v137, -v134, v135, 1.0
	v_fmac_f32_e32 v135, v137, v135
	v_mul_f32_e32 v138, v136, v135
	v_fma_f32 v137, -v134, v138, v136
	v_fmac_f32_e32 v138, v137, v135
	v_fma_f32 v134, -v134, v138, v136
	v_div_fmas_f32 v134, v134, v135, v138
	v_div_fixup_f32 v134, v134, v133, v70
	v_mul_f32_e32 v134, v78, v134
	v_med3_f32 v134, v134, s57, v194
	v_cvt_f16_f32_e32 v140, v134
	global_store_short v246, v139, s[100:101]
	global_store_short v246, v140, s[100:101] offset:32
	s_add_u32 s100, s98, 0x5c200
	s_addc_u32 s101, s99, 0
	v_mul_f32_e32 v132, 0xbfb8aa3b, v67
	v_exp_f32_e32 v132, v132
	s_nop 0
	v_add_f32_e32 v133, 1.0, v132
	v_div_scale_f32 v134, s[2:3], v133, v133, v67
	v_rcp_f32_e32 v135, v134
	v_div_scale_f32 v136, vcc, v67, v133, v67
	v_fma_f32 v137, -v134, v135, 1.0
	v_fmac_f32_e32 v135, v137, v135
	v_mul_f32_e32 v138, v136, v135
	v_fma_f32 v137, -v134, v138, v136
	v_fmac_f32_e32 v138, v137, v135
	v_fma_f32 v134, -v134, v138, v136
	v_div_fmas_f32 v134, v134, v135, v138
	v_div_fixup_f32 v134, v134, v133, v67
	v_mul_f32_e32 v134, v75, v134
	v_med3_f32 v134, v134, s57, v194
	v_cvt_f16_f32_e32 v139, v134
	v_mul_f32_e32 v132, 0xbfb8aa3b, v71
	v_exp_f32_e32 v132, v132
	s_nop 0
	v_add_f32_e32 v133, 1.0, v132
	v_div_scale_f32 v134, s[2:3], v133, v133, v71
	v_rcp_f32_e32 v135, v134
	v_div_scale_f32 v136, vcc, v71, v133, v71
	v_fma_f32 v137, -v134, v135, 1.0
	v_fmac_f32_e32 v135, v137, v135
	v_mul_f32_e32 v138, v136, v135
	v_fma_f32 v137, -v134, v138, v136
	v_fmac_f32_e32 v138, v137, v135
	v_fma_f32 v134, -v134, v138, v136
	v_div_fmas_f32 v134, v134, v135, v138
	v_div_fixup_f32 v134, v134, v133, v71
	v_mul_f32_e32 v134, v79, v134
	v_med3_f32 v134, v134, s57, v194
	v_cvt_f16_f32_e32 v140, v134
	global_store_short v246, v139, s[100:101]
	global_store_short v246, v140, s[100:101] offset:32
	s_add_u32 s100, s98, 0x6e000
	s_addc_u32 s101, s99, 0
	v_mul_f32_e32 v132, 0xbfb8aa3b, v80
	v_exp_f32_e32 v132, v132
	s_nop 0
	v_add_f32_e32 v133, 1.0, v132
	v_div_scale_f32 v134, s[2:3], v133, v133, v80
	v_rcp_f32_e32 v135, v134
	v_div_scale_f32 v136, vcc, v80, v133, v80
	v_fma_f32 v137, -v134, v135, 1.0
	v_fmac_f32_e32 v135, v137, v135
	v_mul_f32_e32 v138, v136, v135
	v_fma_f32 v137, -v134, v138, v136
	v_fmac_f32_e32 v138, v137, v135
	v_fma_f32 v134, -v134, v138, v136
	v_div_fmas_f32 v134, v134, v135, v138
	v_div_fixup_f32 v134, v134, v133, v80
	v_mul_f32_e32 v134, v88, v134
	v_med3_f32 v134, v134, s57, v194
	v_cvt_f16_f32_e32 v139, v134
	v_mul_f32_e32 v132, 0xbfb8aa3b, v84
	v_exp_f32_e32 v132, v132
	s_nop 0
	v_add_f32_e32 v133, 1.0, v132
	v_div_scale_f32 v134, s[2:3], v133, v133, v84
	v_rcp_f32_e32 v135, v134
	v_div_scale_f32 v136, vcc, v84, v133, v84
	v_fma_f32 v137, -v134, v135, 1.0
	v_fmac_f32_e32 v135, v137, v135
	v_mul_f32_e32 v138, v136, v135
	v_fma_f32 v137, -v134, v138, v136
	v_fmac_f32_e32 v138, v137, v135
	v_fma_f32 v134, -v134, v138, v136
	v_div_fmas_f32 v134, v134, v135, v138
	v_div_fixup_f32 v134, v134, v133, v84
	v_mul_f32_e32 v134, v92, v134
	v_med3_f32 v134, v134, s57, v194
	v_cvt_f16_f32_e32 v140, v134
	global_store_short v246, v139, s[100:101]
	global_store_short v246, v140, s[100:101] offset:32
	s_add_u32 s100, s98, 0x6f600
	s_addc_u32 s101, s99, 0
	v_mul_f32_e32 v132, 0xbfb8aa3b, v81
	v_exp_f32_e32 v132, v132
	s_nop 0
	v_add_f32_e32 v133, 1.0, v132
	v_div_scale_f32 v134, s[2:3], v133, v133, v81
	v_rcp_f32_e32 v135, v134
	v_div_scale_f32 v136, vcc, v81, v133, v81
	v_fma_f32 v137, -v134, v135, 1.0
	v_fmac_f32_e32 v135, v137, v135
	v_mul_f32_e32 v138, v136, v135
	v_fma_f32 v137, -v134, v138, v136
	v_fmac_f32_e32 v138, v137, v135
	v_fma_f32 v134, -v134, v138, v136
	v_div_fmas_f32 v134, v134, v135, v138
	v_div_fixup_f32 v134, v134, v133, v81
	v_mul_f32_e32 v134, v89, v134
	v_med3_f32 v134, v134, s57, v194
	v_cvt_f16_f32_e32 v139, v134
	v_mul_f32_e32 v132, 0xbfb8aa3b, v85
	v_exp_f32_e32 v132, v132
	s_nop 0
	v_add_f32_e32 v133, 1.0, v132
	v_div_scale_f32 v134, s[2:3], v133, v133, v85
	v_rcp_f32_e32 v135, v134
	v_div_scale_f32 v136, vcc, v85, v133, v85
	v_fma_f32 v137, -v134, v135, 1.0
	v_fmac_f32_e32 v135, v137, v135
	v_mul_f32_e32 v138, v136, v135
	v_fma_f32 v137, -v134, v138, v136
	v_fmac_f32_e32 v138, v137, v135
	v_fma_f32 v134, -v134, v138, v136
	v_div_fmas_f32 v134, v134, v135, v138
	v_div_fixup_f32 v134, v134, v133, v85
	v_mul_f32_e32 v134, v93, v134
	v_med3_f32 v134, v134, s57, v194
	v_cvt_f16_f32_e32 v140, v134
	global_store_short v246, v139, s[100:101]
	global_store_short v246, v140, s[100:101] offset:32
	s_add_u32 s100, s98, 0x70c00
	s_addc_u32 s101, s99, 0
	v_mul_f32_e32 v132, 0xbfb8aa3b, v82
	v_exp_f32_e32 v132, v132
	s_nop 0
	v_add_f32_e32 v133, 1.0, v132
	v_div_scale_f32 v134, s[2:3], v133, v133, v82
	v_rcp_f32_e32 v135, v134
	v_div_scale_f32 v136, vcc, v82, v133, v82
	v_fma_f32 v137, -v134, v135, 1.0
	v_fmac_f32_e32 v135, v137, v135
	v_mul_f32_e32 v138, v136, v135
	v_fma_f32 v137, -v134, v138, v136
	v_fmac_f32_e32 v138, v137, v135
	v_fma_f32 v134, -v134, v138, v136
	v_div_fmas_f32 v134, v134, v135, v138
	v_div_fixup_f32 v134, v134, v133, v82
	v_mul_f32_e32 v134, v90, v134
	v_med3_f32 v134, v134, s57, v194
	v_cvt_f16_f32_e32 v139, v134
	v_mul_f32_e32 v132, 0xbfb8aa3b, v86
	v_exp_f32_e32 v132, v132
	s_nop 0
	v_add_f32_e32 v133, 1.0, v132
	v_div_scale_f32 v134, s[2:3], v133, v133, v86
	v_rcp_f32_e32 v135, v134
	v_div_scale_f32 v136, vcc, v86, v133, v86
	v_fma_f32 v137, -v134, v135, 1.0
	v_fmac_f32_e32 v135, v137, v135
	v_mul_f32_e32 v138, v136, v135
	v_fma_f32 v137, -v134, v138, v136
	v_fmac_f32_e32 v138, v137, v135
	v_fma_f32 v134, -v134, v138, v136
	v_div_fmas_f32 v134, v134, v135, v138
	v_div_fixup_f32 v134, v134, v133, v86
	v_mul_f32_e32 v134, v94, v134
	v_med3_f32 v134, v134, s57, v194
	v_cvt_f16_f32_e32 v140, v134
	global_store_short v246, v139, s[100:101]
	global_store_short v246, v140, s[100:101] offset:32
	s_add_u32 s100, s98, 0x72200
	s_addc_u32 s101, s99, 0
	v_mul_f32_e32 v132, 0xbfb8aa3b, v83
	v_exp_f32_e32 v132, v132
	s_nop 0
	v_add_f32_e32 v133, 1.0, v132
	v_div_scale_f32 v134, s[2:3], v133, v133, v83
	v_rcp_f32_e32 v135, v134
	v_div_scale_f32 v136, vcc, v83, v133, v83
	v_fma_f32 v137, -v134, v135, 1.0
	v_fmac_f32_e32 v135, v137, v135
	v_mul_f32_e32 v138, v136, v135
	v_fma_f32 v137, -v134, v138, v136
	v_fmac_f32_e32 v138, v137, v135
	v_fma_f32 v134, -v134, v138, v136
	v_div_fmas_f32 v134, v134, v135, v138
	v_div_fixup_f32 v134, v134, v133, v83
	v_mul_f32_e32 v134, v91, v134
	v_med3_f32 v134, v134, s57, v194
	v_cvt_f16_f32_e32 v139, v134
	v_mul_f32_e32 v132, 0xbfb8aa3b, v87
	v_exp_f32_e32 v132, v132
	s_nop 0
	v_add_f32_e32 v133, 1.0, v132
	v_div_scale_f32 v134, s[2:3], v133, v133, v87
	v_rcp_f32_e32 v135, v134
	v_div_scale_f32 v136, vcc, v87, v133, v87
	v_fma_f32 v137, -v134, v135, 1.0
	v_fmac_f32_e32 v135, v137, v135
	v_mul_f32_e32 v138, v136, v135
	v_fma_f32 v137, -v134, v138, v136
	v_fmac_f32_e32 v138, v137, v135
	v_fma_f32 v134, -v134, v138, v136
	v_div_fmas_f32 v134, v134, v135, v138
	v_div_fixup_f32 v134, v134, v133, v87
	v_mul_f32_e32 v134, v95, v134
	v_med3_f32 v134, v134, s57, v194
	v_cvt_f16_f32_e32 v140, v134
	global_store_short v246, v139, s[100:101]
	global_store_short v246, v140, s[100:101] offset:32
	s_add_u32 s100, s98, 0x84000
	s_addc_u32 s101, s99, 0
	v_mul_f32_e32 v132, 0xbfb8aa3b, v96
	v_exp_f32_e32 v132, v132
	s_nop 0
	v_add_f32_e32 v133, 1.0, v132
	v_div_scale_f32 v134, s[2:3], v133, v133, v96
	v_rcp_f32_e32 v135, v134
	v_div_scale_f32 v136, vcc, v96, v133, v96
	v_fma_f32 v137, -v134, v135, 1.0
	v_fmac_f32_e32 v135, v137, v135
	v_mul_f32_e32 v138, v136, v135
	v_fma_f32 v137, -v134, v138, v136
	v_fmac_f32_e32 v138, v137, v135
	v_fma_f32 v134, -v134, v138, v136
	v_div_fmas_f32 v134, v134, v135, v138
	v_div_fixup_f32 v134, v134, v133, v96
	v_mul_f32_e32 v134, v104, v134
	v_med3_f32 v134, v134, s57, v194
	v_cvt_f16_f32_e32 v139, v134
	v_mul_f32_e32 v132, 0xbfb8aa3b, v100
	v_exp_f32_e32 v132, v132
	s_nop 0
	v_add_f32_e32 v133, 1.0, v132
	v_div_scale_f32 v134, s[2:3], v133, v133, v100
	v_rcp_f32_e32 v135, v134
	v_div_scale_f32 v136, vcc, v100, v133, v100
	v_fma_f32 v137, -v134, v135, 1.0
	v_fmac_f32_e32 v135, v137, v135
	v_mul_f32_e32 v138, v136, v135
	v_fma_f32 v137, -v134, v138, v136
	v_fmac_f32_e32 v138, v137, v135
	v_fma_f32 v134, -v134, v138, v136
	v_div_fmas_f32 v134, v134, v135, v138
	v_div_fixup_f32 v134, v134, v133, v100
	v_mul_f32_e32 v134, v108, v134
	v_med3_f32 v134, v134, s57, v194
	v_cvt_f16_f32_e32 v140, v134
	global_store_short v246, v139, s[100:101]
	global_store_short v246, v140, s[100:101] offset:32
	s_add_u32 s100, s98, 0x85600
	s_addc_u32 s101, s99, 0
	v_mul_f32_e32 v132, 0xbfb8aa3b, v97
	v_exp_f32_e32 v132, v132
	s_nop 0
	v_add_f32_e32 v133, 1.0, v132
	v_div_scale_f32 v134, s[2:3], v133, v133, v97
	v_rcp_f32_e32 v135, v134
	v_div_scale_f32 v136, vcc, v97, v133, v97
	v_fma_f32 v137, -v134, v135, 1.0
	v_fmac_f32_e32 v135, v137, v135
	v_mul_f32_e32 v138, v136, v135
	v_fma_f32 v137, -v134, v138, v136
	v_fmac_f32_e32 v138, v137, v135
	v_fma_f32 v134, -v134, v138, v136
	v_div_fmas_f32 v134, v134, v135, v138
	v_div_fixup_f32 v134, v134, v133, v97
	v_mul_f32_e32 v134, v105, v134
	v_med3_f32 v134, v134, s57, v194
	v_cvt_f16_f32_e32 v139, v134
	v_mul_f32_e32 v132, 0xbfb8aa3b, v101
	v_exp_f32_e32 v132, v132
	s_nop 0
	v_add_f32_e32 v133, 1.0, v132
	v_div_scale_f32 v134, s[2:3], v133, v133, v101
	v_rcp_f32_e32 v135, v134
	v_div_scale_f32 v136, vcc, v101, v133, v101
	v_fma_f32 v137, -v134, v135, 1.0
	v_fmac_f32_e32 v135, v137, v135
	v_mul_f32_e32 v138, v136, v135
	v_fma_f32 v137, -v134, v138, v136
	v_fmac_f32_e32 v138, v137, v135
	v_fma_f32 v134, -v134, v138, v136
	v_div_fmas_f32 v134, v134, v135, v138
	v_div_fixup_f32 v134, v134, v133, v101
	v_mul_f32_e32 v134, v109, v134
	v_med3_f32 v134, v134, s57, v194
	v_cvt_f16_f32_e32 v140, v134
	global_store_short v246, v139, s[100:101]
	global_store_short v246, v140, s[100:101] offset:32
	s_add_u32 s100, s98, 0x86c00
	s_addc_u32 s101, s99, 0
	v_mul_f32_e32 v132, 0xbfb8aa3b, v98
	v_exp_f32_e32 v132, v132
	s_nop 0
	v_add_f32_e32 v133, 1.0, v132
	v_div_scale_f32 v134, s[2:3], v133, v133, v98
	v_rcp_f32_e32 v135, v134
	v_div_scale_f32 v136, vcc, v98, v133, v98
	v_fma_f32 v137, -v134, v135, 1.0
	v_fmac_f32_e32 v135, v137, v135
	v_mul_f32_e32 v138, v136, v135
	v_fma_f32 v137, -v134, v138, v136
	v_fmac_f32_e32 v138, v137, v135
	v_fma_f32 v134, -v134, v138, v136
	v_div_fmas_f32 v134, v134, v135, v138
	v_div_fixup_f32 v134, v134, v133, v98
	v_mul_f32_e32 v134, v106, v134
	v_med3_f32 v134, v134, s57, v194
	v_cvt_f16_f32_e32 v139, v134
	v_mul_f32_e32 v132, 0xbfb8aa3b, v102
	v_exp_f32_e32 v132, v132
	s_nop 0
	v_add_f32_e32 v133, 1.0, v132
	v_div_scale_f32 v134, s[2:3], v133, v133, v102
	v_rcp_f32_e32 v135, v134
	v_div_scale_f32 v136, vcc, v102, v133, v102
	v_fma_f32 v137, -v134, v135, 1.0
	v_fmac_f32_e32 v135, v137, v135
	v_mul_f32_e32 v138, v136, v135
	v_fma_f32 v137, -v134, v138, v136
	v_fmac_f32_e32 v138, v137, v135
	v_fma_f32 v134, -v134, v138, v136
	v_div_fmas_f32 v134, v134, v135, v138
	v_div_fixup_f32 v134, v134, v133, v102
	v_mul_f32_e32 v134, v110, v134
	v_med3_f32 v134, v134, s57, v194
	v_cvt_f16_f32_e32 v140, v134
	global_store_short v246, v139, s[100:101]
	global_store_short v246, v140, s[100:101] offset:32
	s_add_u32 s100, s98, 0x88200
	s_addc_u32 s101, s99, 0
	v_mul_f32_e32 v132, 0xbfb8aa3b, v99
	v_exp_f32_e32 v132, v132
	s_nop 0
	v_add_f32_e32 v133, 1.0, v132
	v_div_scale_f32 v134, s[2:3], v133, v133, v99
	v_rcp_f32_e32 v135, v134
	v_div_scale_f32 v136, vcc, v99, v133, v99
	v_fma_f32 v137, -v134, v135, 1.0
	v_fmac_f32_e32 v135, v137, v135
	v_mul_f32_e32 v138, v136, v135
	v_fma_f32 v137, -v134, v138, v136
	v_fmac_f32_e32 v138, v137, v135
	v_fma_f32 v134, -v134, v138, v136
	v_div_fmas_f32 v134, v134, v135, v138
	v_div_fixup_f32 v134, v134, v133, v99
	v_mul_f32_e32 v134, v107, v134
	v_med3_f32 v134, v134, s57, v194
	v_cvt_f16_f32_e32 v139, v134
	v_mul_f32_e32 v132, 0xbfb8aa3b, v103
	v_exp_f32_e32 v132, v132
	s_nop 0
	v_add_f32_e32 v133, 1.0, v132
	v_div_scale_f32 v134, s[2:3], v133, v133, v103
	v_rcp_f32_e32 v135, v134
	v_div_scale_f32 v136, vcc, v103, v133, v103
	v_fma_f32 v137, -v134, v135, 1.0
	v_fmac_f32_e32 v135, v137, v135
	v_mul_f32_e32 v138, v136, v135
	v_fma_f32 v137, -v134, v138, v136
	v_fmac_f32_e32 v138, v137, v135
	v_fma_f32 v134, -v134, v138, v136
	v_div_fmas_f32 v134, v134, v135, v138
	v_div_fixup_f32 v134, v134, v133, v103
	v_mul_f32_e32 v134, v111, v134
	v_med3_f32 v134, v134, s57, v194
	v_cvt_f16_f32_e32 v140, v134
	global_store_short v246, v139, s[100:101]
	global_store_short v246, v140, s[100:101] offset:32
	s_add_u32 s100, s98, 0x9a000
	s_addc_u32 s101, s99, 0
	v_mul_f32_e32 v132, 0xbfb8aa3b, v116
	v_exp_f32_e32 v132, v132
	s_nop 0
	v_add_f32_e32 v133, 1.0, v132
	v_div_scale_f32 v134, s[2:3], v133, v133, v116
	v_rcp_f32_e32 v135, v134
	v_div_scale_f32 v136, vcc, v116, v133, v116
	v_fma_f32 v137, -v134, v135, 1.0
	v_fmac_f32_e32 v135, v137, v135
	v_mul_f32_e32 v138, v136, v135
	v_fma_f32 v137, -v134, v138, v136
	v_fmac_f32_e32 v138, v137, v135
	v_fma_f32 v134, -v134, v138, v136
	v_div_fmas_f32 v134, v134, v135, v138
	v_div_fixup_f32 v134, v134, v133, v116
	v_mul_f32_e32 v134, v124, v134
	v_med3_f32 v134, v134, s57, v194
	v_cvt_f16_f32_e32 v139, v134
	v_mul_f32_e32 v132, 0xbfb8aa3b, v120
	v_exp_f32_e32 v132, v132
	s_nop 0
	v_add_f32_e32 v133, 1.0, v132
	v_div_scale_f32 v134, s[2:3], v133, v133, v120
	v_rcp_f32_e32 v135, v134
	v_div_scale_f32 v136, vcc, v120, v133, v120
	v_fma_f32 v137, -v134, v135, 1.0
	v_fmac_f32_e32 v135, v137, v135
	v_mul_f32_e32 v138, v136, v135
	v_fma_f32 v137, -v134, v138, v136
	v_fmac_f32_e32 v138, v137, v135
	v_fma_f32 v134, -v134, v138, v136
	v_div_fmas_f32 v134, v134, v135, v138
	v_div_fixup_f32 v134, v134, v133, v120
	v_mul_f32_e32 v134, v128, v134
	v_med3_f32 v134, v134, s57, v194
	v_cvt_f16_f32_e32 v140, v134
	global_store_short v246, v139, s[100:101]
	global_store_short v246, v140, s[100:101] offset:32
	s_add_u32 s100, s98, 0x9b600
	s_addc_u32 s101, s99, 0
	v_mul_f32_e32 v132, 0xbfb8aa3b, v117
	v_exp_f32_e32 v132, v132
	s_nop 0
	v_add_f32_e32 v133, 1.0, v132
	v_div_scale_f32 v134, s[2:3], v133, v133, v117
	v_rcp_f32_e32 v135, v134
	v_div_scale_f32 v136, vcc, v117, v133, v117
	v_fma_f32 v137, -v134, v135, 1.0
	v_fmac_f32_e32 v135, v137, v135
	v_mul_f32_e32 v138, v136, v135
	v_fma_f32 v137, -v134, v138, v136
	v_fmac_f32_e32 v138, v137, v135
	v_fma_f32 v134, -v134, v138, v136
	v_div_fmas_f32 v134, v134, v135, v138
	v_div_fixup_f32 v134, v134, v133, v117
	v_mul_f32_e32 v134, v125, v134
	v_med3_f32 v134, v134, s57, v194
	v_cvt_f16_f32_e32 v139, v134
	v_mul_f32_e32 v132, 0xbfb8aa3b, v121
	v_exp_f32_e32 v132, v132
	s_nop 0
	v_add_f32_e32 v133, 1.0, v132
	v_div_scale_f32 v134, s[2:3], v133, v133, v121
	v_rcp_f32_e32 v135, v134
	v_div_scale_f32 v136, vcc, v121, v133, v121
	v_fma_f32 v137, -v134, v135, 1.0
	v_fmac_f32_e32 v135, v137, v135
	v_mul_f32_e32 v138, v136, v135
	v_fma_f32 v137, -v134, v138, v136
	v_fmac_f32_e32 v138, v137, v135
	v_fma_f32 v134, -v134, v138, v136
	v_div_fmas_f32 v134, v134, v135, v138
	v_div_fixup_f32 v134, v134, v133, v121
	v_mul_f32_e32 v134, v129, v134
	v_med3_f32 v134, v134, s57, v194
	v_cvt_f16_f32_e32 v140, v134
	global_store_short v246, v139, s[100:101]
	global_store_short v246, v140, s[100:101] offset:32
	s_add_u32 s100, s98, 0x9cc00
	s_addc_u32 s101, s99, 0
	v_mul_f32_e32 v132, 0xbfb8aa3b, v118
	v_exp_f32_e32 v132, v132
	s_nop 0
	v_add_f32_e32 v133, 1.0, v132
	v_div_scale_f32 v134, s[2:3], v133, v133, v118
	v_rcp_f32_e32 v135, v134
	v_div_scale_f32 v136, vcc, v118, v133, v118
	v_fma_f32 v137, -v134, v135, 1.0
	v_fmac_f32_e32 v135, v137, v135
	v_mul_f32_e32 v138, v136, v135
	v_fma_f32 v137, -v134, v138, v136
	v_fmac_f32_e32 v138, v137, v135
	v_fma_f32 v134, -v134, v138, v136
	v_div_fmas_f32 v134, v134, v135, v138
	v_div_fixup_f32 v134, v134, v133, v118
	v_mul_f32_e32 v134, v126, v134
	v_med3_f32 v134, v134, s57, v194
	v_cvt_f16_f32_e32 v139, v134
	v_mul_f32_e32 v132, 0xbfb8aa3b, v122
	v_exp_f32_e32 v132, v132
	s_nop 0
	v_add_f32_e32 v133, 1.0, v132
	v_div_scale_f32 v134, s[2:3], v133, v133, v122
	v_rcp_f32_e32 v135, v134
	v_div_scale_f32 v136, vcc, v122, v133, v122
	v_fma_f32 v137, -v134, v135, 1.0
	v_fmac_f32_e32 v135, v137, v135
	v_mul_f32_e32 v138, v136, v135
	v_fma_f32 v137, -v134, v138, v136
	v_fmac_f32_e32 v138, v137, v135
	v_fma_f32 v134, -v134, v138, v136
	v_div_fmas_f32 v134, v134, v135, v138
	v_div_fixup_f32 v134, v134, v133, v122
	v_mul_f32_e32 v134, v130, v134
	v_med3_f32 v134, v134, s57, v194
	v_cvt_f16_f32_e32 v140, v134
	global_store_short v246, v139, s[100:101]
	global_store_short v246, v140, s[100:101] offset:32
	s_add_u32 s100, s98, 0x9e200
	s_addc_u32 s101, s99, 0
	v_mul_f32_e32 v132, 0xbfb8aa3b, v119
	v_exp_f32_e32 v132, v132
	s_nop 0
	v_add_f32_e32 v133, 1.0, v132
	v_div_scale_f32 v134, s[2:3], v133, v133, v119
	v_rcp_f32_e32 v135, v134
	v_div_scale_f32 v136, vcc, v119, v133, v119
	v_fma_f32 v137, -v134, v135, 1.0
	v_fmac_f32_e32 v135, v137, v135
	v_mul_f32_e32 v138, v136, v135
	v_fma_f32 v137, -v134, v138, v136
	v_fmac_f32_e32 v138, v137, v135
	v_fma_f32 v134, -v134, v138, v136
	v_div_fmas_f32 v134, v134, v135, v138
	v_div_fixup_f32 v134, v134, v133, v119
	v_mul_f32_e32 v134, v127, v134
	v_med3_f32 v134, v134, s57, v194
	v_cvt_f16_f32_e32 v139, v134
	v_mul_f32_e32 v132, 0xbfb8aa3b, v123
	v_exp_f32_e32 v132, v132
	s_nop 0
	v_add_f32_e32 v133, 1.0, v132
	v_div_scale_f32 v134, s[2:3], v133, v133, v123
	v_rcp_f32_e32 v135, v134
	v_div_scale_f32 v136, vcc, v123, v133, v123
	v_fma_f32 v137, -v134, v135, 1.0
	v_fmac_f32_e32 v135, v137, v135
	v_mul_f32_e32 v138, v136, v135
	v_fma_f32 v137, -v134, v138, v136
	v_fmac_f32_e32 v138, v137, v135
	v_fma_f32 v134, -v134, v138, v136
	v_div_fmas_f32 v134, v134, v135, v138
	v_div_fixup_f32 v134, v134, v133, v123
	v_mul_f32_e32 v134, v131, v134
	v_med3_f32 v134, v134, s57, v194
	v_cvt_f16_f32_e32 v140, v134
	global_store_short v246, v139, s[100:101]
	global_store_short v246, v140, s[100:101] offset:32
	s_add_i32 s10, s10, s60
	s_lshr_b32 s4, s62, 1
	s_cmp_ge_i32 s10, s4
	s_cbranch_scc0 .LBB0_631
	v_mov_b32_e32 v113, 0
	v_mov_b32_e32 v114, 0x3f317218
